# v88 + weight-convert filler (3 instances x 6 transpose loops): 16 loads per loop body issued before the LDS writes (were 8 serialized 2-load round trips), counted vmcnt waits
# baseline (speedup 1.0000x reference)
.LBB0_135:
	s_lshl_b32 s8, s5, 1
	s_lshl_b32 s7, s4, 1
	v_or_b32_e32 v44, s8, v34
	v_or_b32_e32 v42, s7, v3
	v_ashrrev_i32_e32 v45, 31, v44
	v_ashrrev_i32_e32 v43, 31, v42
	v_lshlrev_b64 v[44:45], 12, v[44:45]
	v_lshlrev_b64 v[42:43], 12, v[42:43]
	v_lshl_add_u64 v[44:45], v[32:33], 0, v[44:45]
	v_lshl_add_u64 v[42:43], v[32:33], 0, v[42:43]
	global_load_dword v226, v[44:45], off
	global_load_dword v227, v[42:43], off
	v_or_b32_e32 v31, s7, v1
	v_or_b32_e32 v36, s8, v2
	v_mad_u64_u32 v[196:197], s[10:11], v36, s22, v[4:5]
	v_mad_u64_u32 v[198:199], s[10:11], v31, s22, v[4:5]
	s_add_i32 s10, s8, 4
	s_add_i32 s9, s7, 4
	v_or_b32_e32 v31, s9, v1
	v_or_b32_e32 v36, s10, v2
	s_add_i32 s5, s5, 16
	s_add_i32 s4, s4, 16
	s_add_i32 s6, s6, -16
	v_or_b32_e32 v44, s10, v34
	v_or_b32_e32 v42, s9, v3
	v_ashrrev_i32_e32 v45, 31, v44
	v_ashrrev_i32_e32 v43, 31, v42
	v_lshlrev_b64 v[44:45], 12, v[44:45]
	v_lshlrev_b64 v[42:43], 12, v[42:43]
	v_lshl_add_u64 v[44:45], v[32:33], 0, v[44:45]
	v_lshl_add_u64 v[42:43], v[32:33], 0, v[42:43]
	global_load_dword v228, v[44:45], off
	global_load_dword v229, v[42:43], off
	v_mad_u64_u32 v[200:201], s[10:11], v36, s22, v[4:5]
	v_mad_u64_u32 v[202:203], s[10:11], v31, s22, v[4:5]
	s_add_i32 s10, s8, 8
	s_add_i32 s9, s7, 8
	v_or_b32_e32 v31, s9, v1
	v_or_b32_e32 v36, s10, v2
	v_or_b32_e32 v44, s10, v34
	v_or_b32_e32 v42, s9, v3
	v_ashrrev_i32_e32 v45, 31, v44
	v_ashrrev_i32_e32 v43, 31, v42
	v_lshlrev_b64 v[44:45], 12, v[44:45]
	v_lshlrev_b64 v[42:43], 12, v[42:43]
	v_lshl_add_u64 v[44:45], v[32:33], 0, v[44:45]
	v_lshl_add_u64 v[42:43], v[32:33], 0, v[42:43]
	global_load_dword v230, v[44:45], off
	global_load_dword v231, v[42:43], off
	v_mad_u64_u32 v[206:207], s[10:11], v36, s22, v[4:5]
	v_mad_u64_u32 v[208:209], s[10:11], v31, s22, v[4:5]
	s_add_i32 s10, s8, 12
	s_add_i32 s9, s7, 12
	v_or_b32_e32 v31, s9, v1
	v_or_b32_e32 v36, s10, v2
	v_or_b32_e32 v44, s10, v34
	v_or_b32_e32 v42, s9, v3
	v_ashrrev_i32_e32 v45, 31, v44
	v_ashrrev_i32_e32 v43, 31, v42
	v_lshlrev_b64 v[44:45], 12, v[44:45]
	v_lshlrev_b64 v[42:43], 12, v[42:43]
	v_lshl_add_u64 v[44:45], v[32:33], 0, v[44:45]
	v_lshl_add_u64 v[42:43], v[32:33], 0, v[42:43]
	global_load_dword v232, v[44:45], off
	global_load_dword v233, v[42:43], off
	v_mad_u64_u32 v[210:211], s[10:11], v36, s22, v[4:5]
	v_mad_u64_u32 v[212:213], s[10:11], v31, s22, v[4:5]
	s_add_i32 s10, s8, 16
	s_add_i32 s9, s7, 16
	v_or_b32_e32 v31, s9, v1
	v_or_b32_e32 v36, s10, v2
	v_or_b32_e32 v44, s10, v34
	v_or_b32_e32 v42, s9, v3
	v_ashrrev_i32_e32 v45, 31, v44
	v_ashrrev_i32_e32 v43, 31, v42
	v_lshlrev_b64 v[44:45], 12, v[44:45]
	v_lshlrev_b64 v[42:43], 12, v[42:43]
	v_lshl_add_u64 v[44:45], v[32:33], 0, v[44:45]
	v_lshl_add_u64 v[42:43], v[32:33], 0, v[42:43]
	global_load_dword v234, v[44:45], off
	global_load_dword v235, v[42:43], off
	v_mad_u64_u32 v[214:215], s[10:11], v36, s22, v[4:5]
	v_mad_u64_u32 v[216:217], s[10:11], v31, s22, v[4:5]
	s_add_i32 s10, s8, 20
	s_add_i32 s9, s7, 20
	v_or_b32_e32 v31, s9, v1
	v_or_b32_e32 v36, s10, v2
	v_or_b32_e32 v44, s10, v34
	v_or_b32_e32 v42, s9, v3
	v_ashrrev_i32_e32 v45, 31, v44
	v_ashrrev_i32_e32 v43, 31, v42
	v_lshlrev_b64 v[44:45], 12, v[44:45]
	v_lshlrev_b64 v[42:43], 12, v[42:43]
	v_lshl_add_u64 v[44:45], v[32:33], 0, v[44:45]
	v_lshl_add_u64 v[42:43], v[32:33], 0, v[42:43]
	global_load_dword v240, v[44:45], off
	global_load_dword v241, v[42:43], off
	v_mad_u64_u32 v[218:219], s[10:11], v36, s22, v[4:5]
	v_mad_u64_u32 v[220:221], s[10:11], v31, s22, v[4:5]
	s_add_i32 s10, s8, 24
	s_add_i32 s9, s7, 24
	v_or_b32_e32 v31, s9, v1
	v_or_b32_e32 v36, s10, v2
	s_add_i32 s8, s8, 28
	s_add_i32 s7, s7, 28
	s_cmp_lg_u32 s6, 0
	v_or_b32_e32 v44, s10, v34
	v_or_b32_e32 v42, s9, v3
	v_ashrrev_i32_e32 v45, 31, v44
	v_ashrrev_i32_e32 v43, 31, v42
	v_lshlrev_b64 v[44:45], 12, v[44:45]
	v_lshlrev_b64 v[42:43], 12, v[42:43]
	v_lshl_add_u64 v[44:45], v[32:33], 0, v[44:45]
	v_lshl_add_u64 v[42:43], v[32:33], 0, v[42:43]
	global_load_dword v242, v[44:45], off
	global_load_dword v243, v[42:43], off
	v_mad_u64_u32 v[222:223], s[10:11], v36, s22, v[4:5]
	v_mad_u64_u32 v[224:225], s[10:11], v31, s22, v[4:5]
	v_or_b32_e32 v36, s8, v2
	v_or_b32_e32 v31, s7, v1
	v_or_b32_e32 v44, s8, v34
	v_or_b32_e32 v42, s7, v3
	v_ashrrev_i32_e32 v45, 31, v44
	v_ashrrev_i32_e32 v43, 31, v42
	v_lshlrev_b64 v[44:45], 12, v[44:45]
	v_lshlrev_b64 v[42:43], 12, v[42:43]
	v_lshl_add_u64 v[44:45], v[32:33], 0, v[44:45]
	v_lshl_add_u64 v[42:43], v[32:33], 0, v[42:43]
	global_load_dword v41, v[44:45], off
	global_load_dword v46, v[42:43], off
	v_mad_u64_u32 v[42:43], s[8:9], v36, s22, v[4:5]
	v_mad_u64_u32 v[44:45], s[8:9], v31, s22, v[4:5]
	s_waitcnt vmcnt(14)
	ds_write_b32 v196, v226
	ds_write_b32 v198, v227
	s_waitcnt vmcnt(12)
	ds_write_b32 v200, v228
	ds_write_b32 v202, v229
	s_waitcnt vmcnt(10)
	ds_write_b32 v206, v230
	ds_write_b32 v208, v231
	s_waitcnt vmcnt(8)
	ds_write_b32 v210, v232
	ds_write_b32 v212, v233
	s_waitcnt vmcnt(6)
	ds_write_b32 v214, v234
	ds_write_b32 v216, v235
	s_waitcnt vmcnt(4)
	ds_write_b32 v218, v240
	ds_write_b32 v220, v241
	s_waitcnt vmcnt(2)
	ds_write_b32 v222, v242
	ds_write_b32 v224, v243
	s_waitcnt vmcnt(0)
	ds_write_b32 v42, v41
	ds_write_b32 v44, v46
	s_cbranch_scc1 .LBB0_135
	s_waitcnt lgkmcnt(0)
	ds_read2_b32 v[44:45], v37 offset0:33 offset1:41
	ds_read2_b32 v[46:47], v37 offset1:8
	ds_read2_b32 v[48:49], v37 offset0:66 offset1:74
	ds_read2_b32 v[50:51], v37 offset0:99 offset1:107
	ds_read2_b32 v[52:53], v37 offset0:132 offset1:140
	ds_read2_b32 v[54:55], v37 offset0:165 offset1:173
	ds_read2_b32 v[56:57], v37 offset0:198 offset1:206
	ds_read2_b32 v[58:59], v37 offset0:231 offset1:239
	v_or_b32_e32 v3, v35, v5
	v_mul_u32_u24_e32 v3, 0xb00, v3
	v_mov_b32_e32 v31, v161
	v_lshlrev_b32_e32 v160, 1, v3
	v_or_b32_e32 v3, v35, v38
	v_lshl_add_u64 v[42:43], v[30:31], 1, v[6:7]
	v_mul_u32_u24_e32 v3, 0xb00, v3
	s_waitcnt lgkmcnt(0)
	v_cvt_pk_bf16_f32 v30, v46, v44
	v_cvt_pk_bf16_f32 v31, v48, v50
	v_cvt_pk_bf16_f32 v32, v52, v54
	v_cvt_pk_bf16_f32 v33, v56, v58
	v_lshl_add_u64 v[60:61], v[42:43], 0, v[160:161]
	v_lshlrev_b32_e32 v160, 1, v3
	global_store_dwordx4 v[60:61], v[30:33], off
	v_or_b32_e32 v3, v35, v39
	v_mul_u32_u24_e32 v3, 0xb00, v3
	v_cvt_pk_bf16_f32 v30, v47, v45
	v_cvt_pk_bf16_f32 v31, v49, v51
	v_cvt_pk_bf16_f32 v32, v53, v55
	v_cvt_pk_bf16_f32 v33, v57, v59
	v_lshl_add_u64 v[44:45], v[42:43], 0, v[160:161]
	global_store_dwordx4 v[44:45], v[30:33], off
	ds_read2_b32 v[44:45], v37 offset0:16 offset1:24
	ds_read2_b32 v[46:47], v37 offset0:49 offset1:57
	ds_read2_b32 v[48:49], v37 offset0:82 offset1:90
	ds_read2_b32 v[50:51], v37 offset0:115 offset1:123
	ds_read2_b32 v[52:53], v37 offset0:148 offset1:156
	ds_read2_b32 v[54:55], v37 offset0:181 offset1:189
	ds_read2_b32 v[56:57], v37 offset0:214 offset1:222
	ds_read2_b32 v[58:59], v37 offset0:247 offset1:255
	v_lshlrev_b32_e32 v160, 1, v3
	v_or_b32_e32 v3, v35, v40
	v_mul_u32_u24_e32 v3, 0xb00, v3
	s_waitcnt lgkmcnt(6)
	v_cvt_pk_bf16_f32 v30, v44, v46
	s_waitcnt lgkmcnt(4)
	v_cvt_pk_bf16_f32 v31, v48, v50
	s_waitcnt lgkmcnt(2)
	v_cvt_pk_bf16_f32 v32, v52, v54
	s_waitcnt lgkmcnt(0)
	v_cvt_pk_bf16_f32 v33, v56, v58
	v_lshl_add_u64 v[60:61], v[42:43], 0, v[160:161]
	v_lshlrev_b32_e32 v160, 1, v3
	global_store_dwordx4 v[60:61], v[30:33], off
	v_lshl_add_u64 v[34:35], v[42:43], 0, v[160:161]
	s_nop 0
	v_cvt_pk_bf16_f32 v30, v45, v47
	v_cvt_pk_bf16_f32 v31, v49, v51
	v_cvt_pk_bf16_f32 v32, v53, v55
	v_cvt_pk_bf16_f32 v33, v57, v59
	global_store_dwordx4 v[34:35], v[30:33], off
	s_waitcnt lgkmcnt(0)

.LBB0_139:
	s_lshl_b32 s10, s7, 1
	s_lshl_b32 s9, s6, 1
	v_or_b32_e32 v42, s10, v32
	v_or_b32_e32 v44, s9, v3
	v_mad_u64_u32 v[42:43], s[12:13], v42, s23, v[30:31]
	v_mad_u64_u32 v[44:45], s[12:13], v44, s23, v[30:31]
	global_load_dword v226, v[42:43], off
	global_load_dword v227, v[44:45], off
	v_or_b32_e32 v36, s9, v1
	v_or_b32_e32 v41, s10, v2
	v_mad_u64_u32 v[196:197], s[12:13], v41, s22, v[4:5]
	v_mad_u64_u32 v[198:199], s[12:13], v36, s22, v[4:5]
	s_add_i32 s12, s10, 4
	s_add_i32 s11, s9, 4
	v_or_b32_e32 v41, s12, v2
	v_or_b32_e32 v36, s11, v1
	s_add_i32 s7, s7, 16
	s_add_i32 s6, s6, 16
	s_add_i32 s8, s8, -16
	v_or_b32_e32 v42, s12, v32
	v_or_b32_e32 v44, s11, v3
	v_mad_u64_u32 v[42:43], s[12:13], v42, s23, v[30:31]
	v_mad_u64_u32 v[44:45], s[12:13], v44, s23, v[30:31]
	global_load_dword v228, v[42:43], off
	global_load_dword v229, v[44:45], off
	v_mad_u64_u32 v[200:201], s[12:13], v41, s22, v[4:5]
	v_mad_u64_u32 v[202:203], s[12:13], v36, s22, v[4:5]
	s_add_i32 s12, s10, 8
	s_add_i32 s11, s9, 8
	v_or_b32_e32 v41, s12, v2
	v_or_b32_e32 v36, s11, v1
	v_or_b32_e32 v42, s12, v32
	v_or_b32_e32 v44, s11, v3
	v_mad_u64_u32 v[42:43], s[12:13], v42, s23, v[30:31]
	v_mad_u64_u32 v[44:45], s[12:13], v44, s23, v[30:31]
	global_load_dword v230, v[42:43], off
	global_load_dword v231, v[44:45], off
	v_mad_u64_u32 v[206:207], s[12:13], v41, s22, v[4:5]
	v_mad_u64_u32 v[208:209], s[12:13], v36, s22, v[4:5]
	s_add_i32 s12, s10, 12
	s_add_i32 s11, s9, 12
	v_or_b32_e32 v41, s12, v2
	v_or_b32_e32 v36, s11, v1
	v_or_b32_e32 v42, s12, v32
	v_or_b32_e32 v44, s11, v3
	v_mad_u64_u32 v[42:43], s[12:13], v42, s23, v[30:31]
	v_mad_u64_u32 v[44:45], s[12:13], v44, s23, v[30:31]
	global_load_dword v232, v[42:43], off
	global_load_dword v233, v[44:45], off
	v_mad_u64_u32 v[210:211], s[12:13], v41, s22, v[4:5]
	v_mad_u64_u32 v[212:213], s[12:13], v36, s22, v[4:5]
	s_add_i32 s12, s10, 16
	s_add_i32 s11, s9, 16
	v_or_b32_e32 v41, s12, v2
	v_or_b32_e32 v36, s11, v1
	v_or_b32_e32 v42, s12, v32
	v_or_b32_e32 v44, s11, v3
	v_mad_u64_u32 v[42:43], s[12:13], v42, s23, v[30:31]
	v_mad_u64_u32 v[44:45], s[12:13], v44, s23, v[30:31]
	global_load_dword v234, v[42:43], off
	global_load_dword v235, v[44:45], off
	v_mad_u64_u32 v[214:215], s[12:13], v41, s22, v[4:5]
	v_mad_u64_u32 v[216:217], s[12:13], v36, s22, v[4:5]
	s_add_i32 s12, s10, 20
	s_add_i32 s11, s9, 20
	v_or_b32_e32 v41, s12, v2
	v_or_b32_e32 v36, s11, v1
	v_or_b32_e32 v42, s12, v32
	v_or_b32_e32 v44, s11, v3
	v_mad_u64_u32 v[42:43], s[12:13], v42, s23, v[30:31]
	v_mad_u64_u32 v[44:45], s[12:13], v44, s23, v[30:31]
	global_load_dword v240, v[42:43], off
	global_load_dword v241, v[44:45], off
	v_mad_u64_u32 v[218:219], s[12:13], v41, s22, v[4:5]
	v_mad_u64_u32 v[220:221], s[12:13], v36, s22, v[4:5]
	s_add_i32 s12, s10, 24
	s_add_i32 s11, s9, 24
	v_or_b32_e32 v41, s12, v2
	v_or_b32_e32 v36, s11, v1
	s_add_i32 s10, s10, 28
	s_add_i32 s9, s9, 28
	s_cmp_lg_u32 s8, 0
	v_or_b32_e32 v42, s12, v32
	v_or_b32_e32 v44, s11, v3
	v_mad_u64_u32 v[42:43], s[12:13], v42, s23, v[30:31]
	v_mad_u64_u32 v[44:45], s[12:13], v44, s23, v[30:31]
	global_load_dword v242, v[42:43], off
	global_load_dword v243, v[44:45], off
	v_mad_u64_u32 v[222:223], s[12:13], v41, s22, v[4:5]
	v_mad_u64_u32 v[224:225], s[12:13], v36, s22, v[4:5]
	v_or_b32_e32 v41, s10, v2
	v_or_b32_e32 v36, s9, v1
	v_or_b32_e32 v42, s10, v32
	v_or_b32_e32 v44, s9, v3
	v_mad_u64_u32 v[42:43], s[10:11], v42, s23, v[30:31]
	v_mad_u64_u32 v[44:45], s[10:11], v44, s23, v[30:31]
	global_load_dword v46, v[42:43], off
	global_load_dword v47, v[44:45], off
	v_mad_u64_u32 v[42:43], s[10:11], v41, s22, v[4:5]
	v_mad_u64_u32 v[44:45], s[10:11], v36, s22, v[4:5]
	s_waitcnt vmcnt(14)
	ds_write_b32 v196, v226
	ds_write_b32 v198, v227
	s_waitcnt vmcnt(12)
	ds_write_b32 v200, v228
	ds_write_b32 v202, v229
	s_waitcnt vmcnt(10)
	ds_write_b32 v206, v230
	ds_write_b32 v208, v231
	s_waitcnt vmcnt(8)
	ds_write_b32 v210, v232
	ds_write_b32 v212, v233
	s_waitcnt vmcnt(6)
	ds_write_b32 v214, v234
	ds_write_b32 v216, v235
	s_waitcnt vmcnt(4)
	ds_write_b32 v218, v240
	ds_write_b32 v220, v241
	s_waitcnt vmcnt(2)
	ds_write_b32 v222, v242
	ds_write_b32 v224, v243
	s_waitcnt vmcnt(0)
	ds_write_b32 v42, v46
	ds_write_b32 v44, v47
	s_cbranch_scc1 .LBB0_139
	s_waitcnt lgkmcnt(0)
	ds_read2_b32 v[30:31], v37 offset0:33 offset1:41
	ds_read2_b32 v[48:49], v37 offset1:8
	s_movk_i32 s6, 0x57
	v_cmp_lt_u16_e32 vcc, s6, v34
	v_mov_b32_e32 v3, 0xfffff500
	ds_read2_b32 v[50:51], v37 offset0:66 offset1:74
	ds_read2_b32 v[52:53], v37 offset0:99 offset1:107
	v_cndmask_b32_e32 v3, 0, v3, vcc
	s_waitcnt lgkmcnt(0)
	v_cvt_pk_bf16_f32 v42, v48, v30
	v_add_lshl_u32 v30, v3, v33, 1
	ds_read2_b32 v[54:55], v37 offset0:132 offset1:140
	ds_read2_b32 v[56:57], v37 offset0:165 offset1:173
	ds_read2_b32 v[58:59], v37 offset0:198 offset1:206
	ds_read2_b32 v[60:61], v37 offset0:231 offset1:239
	v_and_b32_e32 v30, 0xffffff00, v30
	v_mov_b32_e32 v32, 0x80
	s_movk_i32 s6, 0x60
	v_cndmask_b32_e32 v32, 0, v32, vcc
	v_and_or_b32 v30, v33, s6, v30
	v_or3_b32 v34, v30, v5, v32
	v_lshlrev_b32_e32 v160, 1, v35
	v_ashrrev_i32_e32 v35, 31, v34
	v_lshl_add_u64 v[46:47], v[8:9], 0, v[160:161]
	v_lshlrev_b64 v[34:35], 11, v[34:35]
	v_or_b32_e32 v30, v38, v33
	v_cvt_pk_bf16_f32 v43, v50, v52
	s_waitcnt lgkmcnt(2)
	v_cvt_pk_bf16_f32 v44, v54, v56
	s_waitcnt lgkmcnt(0)
	v_cvt_pk_bf16_f32 v45, v58, v60
	v_lshl_add_u64 v[34:35], v[46:47], 0, v[34:35]
	v_add_lshl_u32 v30, v30, v3, 1
	s_movk_i32 s6, 0x6f
	global_store_dwordx4 v[34:35], v[42:45], off
	v_and_b32_e32 v30, 0xffffff00, v30
	s_nop 0
	v_cvt_pk_bf16_f32 v42, v49, v31
	v_bitop3_b32 v31, v38, s6, v33 bitop3:0xc8
	v_or3_b32 v30, v31, v30, v32
	v_ashrrev_i32_e32 v31, 31, v30
	v_lshlrev_b64 v[30:31], 11, v[30:31]
	v_cvt_pk_bf16_f32 v43, v51, v53
	v_cvt_pk_bf16_f32 v44, v55, v57
	v_cvt_pk_bf16_f32 v45, v59, v61
	v_lshl_add_u64 v[30:31], v[46:47], 0, v[30:31]
	global_store_dwordx4 v[30:31], v[42:45], off
	ds_read2_b32 v[30:31], v37 offset0:49 offset1:57
	ds_read2_b32 v[34:35], v37 offset0:16 offset1:24
	s_movk_i32 s6, 0x77
	ds_read2_b32 v[48:49], v37 offset0:82 offset1:90
	ds_read2_b32 v[50:51], v37 offset0:115 offset1:123
	ds_read2_b32 v[52:53], v37 offset0:148 offset1:156
	ds_read2_b32 v[54:55], v37 offset0:181 offset1:189
	ds_read2_b32 v[56:57], v37 offset0:214 offset1:222
	ds_read2_b32 v[58:59], v37 offset0:247 offset1:255
	s_waitcnt lgkmcnt(6)
	v_cvt_pk_bf16_f32 v42, v34, v30
	v_or_b32_e32 v30, v39, v33
	v_add_lshl_u32 v30, v30, v3, 1
	v_and_b32_e32 v30, 0xffffff00, v30
	v_bitop3_b32 v34, v39, s6, v33 bitop3:0xc8
	v_or3_b32 v60, v34, v30, v32
	v_or_b32_e32 v30, v40, v33
	v_add_lshl_u32 v3, v30, v3, 1
	s_movk_i32 s6, 0x7f
	v_and_b32_e32 v3, 0xffffff00, v3
	v_bitop3_b32 v30, v40, s6, v33 bitop3:0xc8
	v_or3_b32 v34, v30, v3, v32
	v_ashrrev_i32_e32 v61, 31, v60
	v_cvt_pk_bf16_f32 v30, v35, v31
	v_ashrrev_i32_e32 v35, 31, v34
	v_lshlrev_b64 v[60:61], 11, v[60:61]
	v_lshlrev_b64 v[34:35], 11, v[34:35]
	s_waitcnt lgkmcnt(4)
	v_cvt_pk_bf16_f32 v43, v48, v50
	s_waitcnt lgkmcnt(2)
	v_cvt_pk_bf16_f32 v44, v52, v54
	s_waitcnt lgkmcnt(0)
	v_cvt_pk_bf16_f32 v45, v56, v58
	v_lshl_add_u64 v[60:61], v[46:47], 0, v[60:61]
	v_cvt_pk_bf16_f32 v31, v49, v51
	v_cvt_pk_bf16_f32 v32, v53, v55
	v_cvt_pk_bf16_f32 v33, v57, v59
	v_lshl_add_u64 v[34:35], v[46:47], 0, v[34:35]
	global_store_dwordx4 v[60:61], v[42:45], off
	global_store_dwordx4 v[34:35], v[30:33], off
	s_waitcnt lgkmcnt(0)

.LBB0_144:
	s_lshl_b32 s8, s5, 1
	s_lshl_b32 s7, s4, 1
	v_or_b32_e32 v44, s8, v34
	v_or_b32_e32 v42, s7, v3
	v_ashrrev_i32_e32 v45, 31, v44
	v_ashrrev_i32_e32 v43, 31, v42
	v_lshlrev_b64 v[44:45], 12, v[44:45]
	v_lshlrev_b64 v[42:43], 12, v[42:43]
	v_lshl_add_u64 v[44:45], v[32:33], 0, v[44:45]
	v_lshl_add_u64 v[42:43], v[32:33], 0, v[42:43]
	global_load_dword v226, v[44:45], off
	global_load_dword v227, v[42:43], off
	v_or_b32_e32 v31, s7, v1
	v_or_b32_e32 v36, s8, v2
	v_mad_u64_u32 v[196:197], s[10:11], v36, s22, v[4:5]
	v_mad_u64_u32 v[198:199], s[10:11], v31, s22, v[4:5]
	s_add_i32 s10, s8, 4
	s_add_i32 s9, s7, 4
	v_or_b32_e32 v31, s9, v1
	v_or_b32_e32 v36, s10, v2
	s_add_i32 s5, s5, 16
	s_add_i32 s4, s4, 16
	s_add_i32 s6, s6, -16
	v_or_b32_e32 v44, s10, v34
	v_or_b32_e32 v42, s9, v3
	v_ashrrev_i32_e32 v45, 31, v44
	v_ashrrev_i32_e32 v43, 31, v42
	v_lshlrev_b64 v[44:45], 12, v[44:45]
	v_lshlrev_b64 v[42:43], 12, v[42:43]
	v_lshl_add_u64 v[44:45], v[32:33], 0, v[44:45]
	v_lshl_add_u64 v[42:43], v[32:33], 0, v[42:43]
	global_load_dword v228, v[44:45], off
	global_load_dword v229, v[42:43], off
	v_mad_u64_u32 v[200:201], s[10:11], v36, s22, v[4:5]
	v_mad_u64_u32 v[202:203], s[10:11], v31, s22, v[4:5]
	s_add_i32 s10, s8, 8
	s_add_i32 s9, s7, 8
	v_or_b32_e32 v31, s9, v1
	v_or_b32_e32 v36, s10, v2
	v_or_b32_e32 v44, s10, v34
	v_or_b32_e32 v42, s9, v3
	v_ashrrev_i32_e32 v45, 31, v44
	v_ashrrev_i32_e32 v43, 31, v42
	v_lshlrev_b64 v[44:45], 12, v[44:45]
	v_lshlrev_b64 v[42:43], 12, v[42:43]
	v_lshl_add_u64 v[44:45], v[32:33], 0, v[44:45]
	v_lshl_add_u64 v[42:43], v[32:33], 0, v[42:43]
	global_load_dword v230, v[44:45], off
	global_load_dword v231, v[42:43], off
	v_mad_u64_u32 v[206:207], s[10:11], v36, s22, v[4:5]
	v_mad_u64_u32 v[208:209], s[10:11], v31, s22, v[4:5]
	s_add_i32 s10, s8, 12
	s_add_i32 s9, s7, 12
	v_or_b32_e32 v31, s9, v1
	v_or_b32_e32 v36, s10, v2
	v_or_b32_e32 v44, s10, v34
	v_or_b32_e32 v42, s9, v3
	v_ashrrev_i32_e32 v45, 31, v44
	v_ashrrev_i32_e32 v43, 31, v42
	v_lshlrev_b64 v[44:45], 12, v[44:45]
	v_lshlrev_b64 v[42:43], 12, v[42:43]
	v_lshl_add_u64 v[44:45], v[32:33], 0, v[44:45]
	v_lshl_add_u64 v[42:43], v[32:33], 0, v[42:43]
	global_load_dword v232, v[44:45], off
	global_load_dword v233, v[42:43], off
	v_mad_u64_u32 v[210:211], s[10:11], v36, s22, v[4:5]
	v_mad_u64_u32 v[212:213], s[10:11], v31, s22, v[4:5]
	s_add_i32 s10, s8, 16
	s_add_i32 s9, s7, 16
	v_or_b32_e32 v31, s9, v1
	v_or_b32_e32 v36, s10, v2
	v_or_b32_e32 v44, s10, v34
	v_or_b32_e32 v42, s9, v3
	v_ashrrev_i32_e32 v45, 31, v44
	v_ashrrev_i32_e32 v43, 31, v42
	v_lshlrev_b64 v[44:45], 12, v[44:45]
	v_lshlrev_b64 v[42:43], 12, v[42:43]
	v_lshl_add_u64 v[44:45], v[32:33], 0, v[44:45]
	v_lshl_add_u64 v[42:43], v[32:33], 0, v[42:43]
	global_load_dword v234, v[44:45], off
	global_load_dword v235, v[42:43], off
	v_mad_u64_u32 v[214:215], s[10:11], v36, s22, v[4:5]
	v_mad_u64_u32 v[216:217], s[10:11], v31, s22, v[4:5]
	s_add_i32 s10, s8, 20
	s_add_i32 s9, s7, 20
	v_or_b32_e32 v31, s9, v1
	v_or_b32_e32 v36, s10, v2
	v_or_b32_e32 v44, s10, v34
	v_or_b32_e32 v42, s9, v3
	v_ashrrev_i32_e32 v45, 31, v44
	v_ashrrev_i32_e32 v43, 31, v42
	v_lshlrev_b64 v[44:45], 12, v[44:45]
	v_lshlrev_b64 v[42:43], 12, v[42:43]
	v_lshl_add_u64 v[44:45], v[32:33], 0, v[44:45]
	v_lshl_add_u64 v[42:43], v[32:33], 0, v[42:43]
	global_load_dword v240, v[44:45], off
	global_load_dword v241, v[42:43], off
	v_mad_u64_u32 v[218:219], s[10:11], v36, s22, v[4:5]
	v_mad_u64_u32 v[220:221], s[10:11], v31, s22, v[4:5]
	s_add_i32 s10, s8, 24
	s_add_i32 s9, s7, 24
	v_or_b32_e32 v31, s9, v1
	v_or_b32_e32 v36, s10, v2
	s_add_i32 s8, s8, 28
	s_add_i32 s7, s7, 28
	s_cmp_lg_u32 s6, 0
	v_or_b32_e32 v44, s10, v34
	v_or_b32_e32 v42, s9, v3
	v_ashrrev_i32_e32 v45, 31, v44
	v_ashrrev_i32_e32 v43, 31, v42
	v_lshlrev_b64 v[44:45], 12, v[44:45]
	v_lshlrev_b64 v[42:43], 12, v[42:43]
	v_lshl_add_u64 v[44:45], v[32:33], 0, v[44:45]
	v_lshl_add_u64 v[42:43], v[32:33], 0, v[42:43]
	global_load_dword v242, v[44:45], off
	global_load_dword v243, v[42:43], off
	v_mad_u64_u32 v[222:223], s[10:11], v36, s22, v[4:5]
	v_mad_u64_u32 v[224:225], s[10:11], v31, s22, v[4:5]
	v_or_b32_e32 v36, s8, v2
	v_or_b32_e32 v31, s7, v1
	v_or_b32_e32 v44, s8, v34
	v_or_b32_e32 v42, s7, v3
	v_ashrrev_i32_e32 v45, 31, v44
	v_ashrrev_i32_e32 v43, 31, v42
	v_lshlrev_b64 v[44:45], 12, v[44:45]
	v_lshlrev_b64 v[42:43], 12, v[42:43]
	v_lshl_add_u64 v[44:45], v[32:33], 0, v[44:45]
	v_lshl_add_u64 v[42:43], v[32:33], 0, v[42:43]
	global_load_dword v41, v[44:45], off
	global_load_dword v46, v[42:43], off
	v_mad_u64_u32 v[42:43], s[8:9], v36, s22, v[4:5]
	v_mad_u64_u32 v[44:45], s[8:9], v31, s22, v[4:5]
	s_waitcnt vmcnt(14)
	ds_write_b32 v196, v226
	ds_write_b32 v198, v227
	s_waitcnt vmcnt(12)
	ds_write_b32 v200, v228
	ds_write_b32 v202, v229
	s_waitcnt vmcnt(10)
	ds_write_b32 v206, v230
	ds_write_b32 v208, v231
	s_waitcnt vmcnt(8)
	ds_write_b32 v210, v232
	ds_write_b32 v212, v233
	s_waitcnt vmcnt(6)
	ds_write_b32 v214, v234
	ds_write_b32 v216, v235
	s_waitcnt vmcnt(4)
	ds_write_b32 v218, v240
	ds_write_b32 v220, v241
	s_waitcnt vmcnt(2)
	ds_write_b32 v222, v242
	ds_write_b32 v224, v243
	s_waitcnt vmcnt(0)
	ds_write_b32 v42, v41
	ds_write_b32 v44, v46
	s_cbranch_scc1 .LBB0_144
	s_waitcnt lgkmcnt(0)
	ds_read2_b32 v[44:45], v37 offset0:33 offset1:41
	ds_read2_b32 v[46:47], v37 offset1:8
	ds_read2_b32 v[48:49], v37 offset0:66 offset1:74
	ds_read2_b32 v[50:51], v37 offset0:99 offset1:107
	ds_read2_b32 v[52:53], v37 offset0:132 offset1:140
	ds_read2_b32 v[54:55], v37 offset0:165 offset1:173
	ds_read2_b32 v[56:57], v37 offset0:198 offset1:206
	ds_read2_b32 v[58:59], v37 offset0:231 offset1:239
	v_mov_b32_e32 v31, v161
	v_or_b32_e32 v3, v35, v5
	v_lshl_add_u64 v[42:43], v[30:31], 1, v[10:11]
	v_lshlrev_b32_e32 v160, 11, v3
	v_or_b32_e32 v3, v35, v38
	s_waitcnt lgkmcnt(0)
	v_cvt_pk_bf16_f32 v30, v46, v44
	v_cvt_pk_bf16_f32 v31, v48, v50
	v_cvt_pk_bf16_f32 v32, v52, v54
	v_cvt_pk_bf16_f32 v33, v56, v58
	v_lshl_add_u64 v[60:61], v[42:43], 0, v[160:161]
	v_lshlrev_b32_e32 v160, 11, v3
	global_store_dwordx4 v[60:61], v[30:33], off
	v_or_b32_e32 v3, v35, v39
	s_nop 0
	v_cvt_pk_bf16_f32 v30, v47, v45
	v_cvt_pk_bf16_f32 v31, v49, v51
	v_cvt_pk_bf16_f32 v32, v53, v55
	v_cvt_pk_bf16_f32 v33, v57, v59
	v_lshl_add_u64 v[44:45], v[42:43], 0, v[160:161]
	global_store_dwordx4 v[44:45], v[30:33], off
	ds_read2_b32 v[44:45], v37 offset0:49 offset1:57
	ds_read2_b32 v[46:47], v37 offset0:16 offset1:24
	ds_read2_b32 v[48:49], v37 offset0:82 offset1:90
	ds_read2_b32 v[50:51], v37 offset0:115 offset1:123
	ds_read2_b32 v[52:53], v37 offset0:148 offset1:156
	ds_read2_b32 v[54:55], v37 offset0:181 offset1:189
	ds_read2_b32 v[56:57], v37 offset0:214 offset1:222
	ds_read2_b32 v[58:59], v37 offset0:247 offset1:255
	v_lshlrev_b32_e32 v160, 11, v3
	v_or_b32_e32 v3, v35, v40
	s_waitcnt lgkmcnt(6)
	v_cvt_pk_bf16_f32 v30, v46, v44
	s_waitcnt lgkmcnt(4)
	v_cvt_pk_bf16_f32 v31, v48, v50
	s_waitcnt lgkmcnt(2)
	v_cvt_pk_bf16_f32 v32, v52, v54
	s_waitcnt lgkmcnt(0)
	v_cvt_pk_bf16_f32 v33, v56, v58
	v_lshl_add_u64 v[60:61], v[42:43], 0, v[160:161]
	v_lshlrev_b32_e32 v160, 11, v3
	global_store_dwordx4 v[60:61], v[30:33], off
	v_lshl_add_u64 v[34:35], v[42:43], 0, v[160:161]
	s_nop 0
	v_cvt_pk_bf16_f32 v30, v47, v45
	v_cvt_pk_bf16_f32 v31, v49, v51
	v_cvt_pk_bf16_f32 v32, v53, v55
	v_cvt_pk_bf16_f32 v33, v57, v59
	global_store_dwordx4 v[34:35], v[30:33], off
	s_waitcnt lgkmcnt(0)

.LBB0_149:
	s_lshl_b32 s8, s5, 1
	s_lshl_b32 s7, s4, 1
	v_or_b32_e32 v44, s8, v34
	v_or_b32_e32 v42, s7, v3
	v_ashrrev_i32_e32 v45, 31, v44
	v_ashrrev_i32_e32 v43, 31, v42
	v_lshlrev_b64 v[44:45], 12, v[44:45]
	v_lshlrev_b64 v[42:43], 12, v[42:43]
	v_lshl_add_u64 v[44:45], v[32:33], 0, v[44:45]
	v_lshl_add_u64 v[42:43], v[32:33], 0, v[42:43]
	global_load_dword v226, v[44:45], off
	global_load_dword v227, v[42:43], off
	v_or_b32_e32 v31, s7, v1
	v_or_b32_e32 v36, s8, v2
	v_mad_u64_u32 v[196:197], s[10:11], v36, s22, v[4:5]
	v_mad_u64_u32 v[198:199], s[10:11], v31, s22, v[4:5]
	s_add_i32 s10, s8, 4
	s_add_i32 s9, s7, 4
	v_or_b32_e32 v31, s9, v1
	v_or_b32_e32 v36, s10, v2
	s_add_i32 s5, s5, 16
	s_add_i32 s4, s4, 16
	s_add_i32 s6, s6, -16
	v_or_b32_e32 v44, s10, v34
	v_or_b32_e32 v42, s9, v3
	v_ashrrev_i32_e32 v45, 31, v44
	v_ashrrev_i32_e32 v43, 31, v42
	v_lshlrev_b64 v[44:45], 12, v[44:45]
	v_lshlrev_b64 v[42:43], 12, v[42:43]
	v_lshl_add_u64 v[44:45], v[32:33], 0, v[44:45]
	v_lshl_add_u64 v[42:43], v[32:33], 0, v[42:43]
	global_load_dword v228, v[44:45], off
	global_load_dword v229, v[42:43], off
	v_mad_u64_u32 v[200:201], s[10:11], v36, s22, v[4:5]
	v_mad_u64_u32 v[202:203], s[10:11], v31, s22, v[4:5]
	s_add_i32 s10, s8, 8
	s_add_i32 s9, s7, 8
	v_or_b32_e32 v31, s9, v1
	v_or_b32_e32 v36, s10, v2
	v_or_b32_e32 v44, s10, v34
	v_or_b32_e32 v42, s9, v3
	v_ashrrev_i32_e32 v45, 31, v44
	v_ashrrev_i32_e32 v43, 31, v42
	v_lshlrev_b64 v[44:45], 12, v[44:45]
	v_lshlrev_b64 v[42:43], 12, v[42:43]
	v_lshl_add_u64 v[44:45], v[32:33], 0, v[44:45]
	v_lshl_add_u64 v[42:43], v[32:33], 0, v[42:43]
	global_load_dword v230, v[44:45], off
	global_load_dword v231, v[42:43], off
	v_mad_u64_u32 v[206:207], s[10:11], v36, s22, v[4:5]
	v_mad_u64_u32 v[208:209], s[10:11], v31, s22, v[4:5]
	s_add_i32 s10, s8, 12
	s_add_i32 s9, s7, 12
	v_or_b32_e32 v31, s9, v1
	v_or_b32_e32 v36, s10, v2
	v_or_b32_e32 v44, s10, v34
	v_or_b32_e32 v42, s9, v3
	v_ashrrev_i32_e32 v45, 31, v44
	v_ashrrev_i32_e32 v43, 31, v42
	v_lshlrev_b64 v[44:45], 12, v[44:45]
	v_lshlrev_b64 v[42:43], 12, v[42:43]
	v_lshl_add_u64 v[44:45], v[32:33], 0, v[44:45]
	v_lshl_add_u64 v[42:43], v[32:33], 0, v[42:43]
	global_load_dword v232, v[44:45], off
	global_load_dword v233, v[42:43], off
	v_mad_u64_u32 v[210:211], s[10:11], v36, s22, v[4:5]
	v_mad_u64_u32 v[212:213], s[10:11], v31, s22, v[4:5]
	s_add_i32 s10, s8, 16
	s_add_i32 s9, s7, 16
	v_or_b32_e32 v31, s9, v1
	v_or_b32_e32 v36, s10, v2
	v_or_b32_e32 v44, s10, v34
	v_or_b32_e32 v42, s9, v3
	v_ashrrev_i32_e32 v45, 31, v44
	v_ashrrev_i32_e32 v43, 31, v42
	v_lshlrev_b64 v[44:45], 12, v[44:45]
	v_lshlrev_b64 v[42:43], 12, v[42:43]
	v_lshl_add_u64 v[44:45], v[32:33], 0, v[44:45]
	v_lshl_add_u64 v[42:43], v[32:33], 0, v[42:43]
	global_load_dword v234, v[44:45], off
	global_load_dword v235, v[42:43], off
	v_mad_u64_u32 v[214:215], s[10:11], v36, s22, v[4:5]
	v_mad_u64_u32 v[216:217], s[10:11], v31, s22, v[4:5]
	s_add_i32 s10, s8, 20
	s_add_i32 s9, s7, 20
	v_or_b32_e32 v31, s9, v1
	v_or_b32_e32 v36, s10, v2
	v_or_b32_e32 v44, s10, v34
	v_or_b32_e32 v42, s9, v3
	v_ashrrev_i32_e32 v45, 31, v44
	v_ashrrev_i32_e32 v43, 31, v42
	v_lshlrev_b64 v[44:45], 12, v[44:45]
	v_lshlrev_b64 v[42:43], 12, v[42:43]
	v_lshl_add_u64 v[44:45], v[32:33], 0, v[44:45]
	v_lshl_add_u64 v[42:43], v[32:33], 0, v[42:43]
	global_load_dword v240, v[44:45], off
	global_load_dword v241, v[42:43], off
	v_mad_u64_u32 v[218:219], s[10:11], v36, s22, v[4:5]
	v_mad_u64_u32 v[220:221], s[10:11], v31, s22, v[4:5]
	s_add_i32 s10, s8, 24
	s_add_i32 s9, s7, 24
	v_or_b32_e32 v31, s9, v1
	v_or_b32_e32 v36, s10, v2
	s_add_i32 s8, s8, 28
	s_add_i32 s7, s7, 28
	s_cmp_lg_u32 s6, 0
	v_or_b32_e32 v44, s10, v34
	v_or_b32_e32 v42, s9, v3
	v_ashrrev_i32_e32 v45, 31, v44
	v_ashrrev_i32_e32 v43, 31, v42
	v_lshlrev_b64 v[44:45], 12, v[44:45]
	v_lshlrev_b64 v[42:43], 12, v[42:43]
	v_lshl_add_u64 v[44:45], v[32:33], 0, v[44:45]
	v_lshl_add_u64 v[42:43], v[32:33], 0, v[42:43]
	global_load_dword v242, v[44:45], off
	global_load_dword v243, v[42:43], off
	v_mad_u64_u32 v[222:223], s[10:11], v36, s22, v[4:5]
	v_mad_u64_u32 v[224:225], s[10:11], v31, s22, v[4:5]
	v_or_b32_e32 v36, s8, v2
	v_or_b32_e32 v31, s7, v1
	v_or_b32_e32 v44, s8, v34
	v_or_b32_e32 v42, s7, v3
	v_ashrrev_i32_e32 v45, 31, v44
	v_ashrrev_i32_e32 v43, 31, v42
	v_lshlrev_b64 v[44:45], 12, v[44:45]
	v_lshlrev_b64 v[42:43], 12, v[42:43]
	v_lshl_add_u64 v[44:45], v[32:33], 0, v[44:45]
	v_lshl_add_u64 v[42:43], v[32:33], 0, v[42:43]
	global_load_dword v41, v[44:45], off
	global_load_dword v46, v[42:43], off
	v_mad_u64_u32 v[42:43], s[8:9], v36, s22, v[4:5]
	v_mad_u64_u32 v[44:45], s[8:9], v31, s22, v[4:5]
	s_waitcnt vmcnt(14)
	ds_write_b32 v196, v226
	ds_write_b32 v198, v227
	s_waitcnt vmcnt(12)
	ds_write_b32 v200, v228
	ds_write_b32 v202, v229
	s_waitcnt vmcnt(10)
	ds_write_b32 v206, v230
	ds_write_b32 v208, v231
	s_waitcnt vmcnt(8)
	ds_write_b32 v210, v232
	ds_write_b32 v212, v233
	s_waitcnt vmcnt(6)
	ds_write_b32 v214, v234
	ds_write_b32 v216, v235
	s_waitcnt vmcnt(4)
	ds_write_b32 v218, v240
	ds_write_b32 v220, v241
	s_waitcnt vmcnt(2)
	ds_write_b32 v222, v242
	ds_write_b32 v224, v243
	s_waitcnt vmcnt(0)
	ds_write_b32 v42, v41
	ds_write_b32 v44, v46
	s_cbranch_scc1 .LBB0_149
	s_waitcnt lgkmcnt(0)
	ds_read2_b32 v[44:45], v37 offset0:33 offset1:41
	ds_read2_b32 v[46:47], v37 offset1:8
	ds_read2_b32 v[48:49], v37 offset0:66 offset1:74
	ds_read2_b32 v[50:51], v37 offset0:99 offset1:107
	ds_read2_b32 v[52:53], v37 offset0:132 offset1:140
	ds_read2_b32 v[54:55], v37 offset0:165 offset1:173
	ds_read2_b32 v[56:57], v37 offset0:198 offset1:206
	ds_read2_b32 v[58:59], v37 offset0:231 offset1:239
	v_mov_b32_e32 v31, v161
	v_or_b32_e32 v3, v35, v5
	v_lshl_add_u64 v[42:43], v[30:31], 1, v[12:13]
	v_lshlrev_b32_e32 v160, 11, v3
	v_or_b32_e32 v3, v35, v38
	s_waitcnt lgkmcnt(0)
	v_cvt_pk_bf16_f32 v30, v46, v44
	v_cvt_pk_bf16_f32 v31, v48, v50
	v_cvt_pk_bf16_f32 v32, v52, v54
	v_cvt_pk_bf16_f32 v33, v56, v58
	v_lshl_add_u64 v[60:61], v[42:43], 0, v[160:161]
	v_lshlrev_b32_e32 v160, 11, v3
	global_store_dwordx4 v[60:61], v[30:33], off
	v_or_b32_e32 v3, v35, v39
	s_nop 0
	v_cvt_pk_bf16_f32 v30, v47, v45
	v_cvt_pk_bf16_f32 v31, v49, v51
	v_cvt_pk_bf16_f32 v32, v53, v55
	v_cvt_pk_bf16_f32 v33, v57, v59
	v_lshl_add_u64 v[44:45], v[42:43], 0, v[160:161]
	global_store_dwordx4 v[44:45], v[30:33], off
	ds_read2_b32 v[44:45], v37 offset0:49 offset1:57
	ds_read2_b32 v[46:47], v37 offset0:16 offset1:24
	ds_read2_b32 v[48:49], v37 offset0:82 offset1:90
	ds_read2_b32 v[50:51], v37 offset0:115 offset1:123
	ds_read2_b32 v[52:53], v37 offset0:148 offset1:156
	ds_read2_b32 v[54:55], v37 offset0:181 offset1:189
	ds_read2_b32 v[56:57], v37 offset0:214 offset1:222
	ds_read2_b32 v[58:59], v37 offset0:247 offset1:255
	v_lshlrev_b32_e32 v160, 11, v3
	v_or_b32_e32 v3, v35, v40
	s_waitcnt lgkmcnt(6)
	v_cvt_pk_bf16_f32 v30, v46, v44
	s_waitcnt lgkmcnt(4)
	v_cvt_pk_bf16_f32 v31, v48, v50
	s_waitcnt lgkmcnt(2)
	v_cvt_pk_bf16_f32 v32, v52, v54
	s_waitcnt lgkmcnt(0)
	v_cvt_pk_bf16_f32 v33, v56, v58
	v_lshl_add_u64 v[60:61], v[42:43], 0, v[160:161]
	v_lshlrev_b32_e32 v160, 11, v3
	global_store_dwordx4 v[60:61], v[30:33], off
	v_lshl_add_u64 v[34:35], v[42:43], 0, v[160:161]
	s_nop 0
	v_cvt_pk_bf16_f32 v30, v47, v45
	v_cvt_pk_bf16_f32 v31, v49, v51
	v_cvt_pk_bf16_f32 v32, v53, v55
	v_cvt_pk_bf16_f32 v33, v57, v59
	global_store_dwordx4 v[34:35], v[30:33], off
	s_waitcnt lgkmcnt(0)

.LBB0_154:
	s_lshl_b32 s8, s5, 1
	s_lshl_b32 s7, s4, 1
	v_or_b32_e32 v44, s8, v34
	v_or_b32_e32 v42, s7, v3
	v_ashrrev_i32_e32 v45, 31, v44
	v_ashrrev_i32_e32 v43, 31, v42
	v_lshlrev_b64 v[44:45], 12, v[44:45]
	v_lshlrev_b64 v[42:43], 12, v[42:43]
	v_lshl_add_u64 v[44:45], v[32:33], 0, v[44:45]
	v_lshl_add_u64 v[42:43], v[32:33], 0, v[42:43]
	global_load_dword v226, v[44:45], off
	global_load_dword v227, v[42:43], off
	v_or_b32_e32 v31, s7, v1
	v_or_b32_e32 v36, s8, v2
	v_mad_u64_u32 v[196:197], s[10:11], v36, s22, v[4:5]
	v_mad_u64_u32 v[198:199], s[10:11], v31, s22, v[4:5]
	s_add_i32 s10, s8, 4
	s_add_i32 s9, s7, 4
	v_or_b32_e32 v31, s9, v1
	v_or_b32_e32 v36, s10, v2
	s_add_i32 s5, s5, 16
	s_add_i32 s4, s4, 16
	s_add_i32 s6, s6, -16
	v_or_b32_e32 v44, s10, v34
	v_or_b32_e32 v42, s9, v3
	v_ashrrev_i32_e32 v45, 31, v44
	v_ashrrev_i32_e32 v43, 31, v42
	v_lshlrev_b64 v[44:45], 12, v[44:45]
	v_lshlrev_b64 v[42:43], 12, v[42:43]
	v_lshl_add_u64 v[44:45], v[32:33], 0, v[44:45]
	v_lshl_add_u64 v[42:43], v[32:33], 0, v[42:43]
	global_load_dword v228, v[44:45], off
	global_load_dword v229, v[42:43], off
	v_mad_u64_u32 v[200:201], s[10:11], v36, s22, v[4:5]
	v_mad_u64_u32 v[202:203], s[10:11], v31, s22, v[4:5]
	s_add_i32 s10, s8, 8
	s_add_i32 s9, s7, 8
	v_or_b32_e32 v31, s9, v1
	v_or_b32_e32 v36, s10, v2
	v_or_b32_e32 v44, s10, v34
	v_or_b32_e32 v42, s9, v3
	v_ashrrev_i32_e32 v45, 31, v44
	v_ashrrev_i32_e32 v43, 31, v42
	v_lshlrev_b64 v[44:45], 12, v[44:45]
	v_lshlrev_b64 v[42:43], 12, v[42:43]
	v_lshl_add_u64 v[44:45], v[32:33], 0, v[44:45]
	v_lshl_add_u64 v[42:43], v[32:33], 0, v[42:43]
	global_load_dword v230, v[44:45], off
	global_load_dword v231, v[42:43], off
	v_mad_u64_u32 v[206:207], s[10:11], v36, s22, v[4:5]
	v_mad_u64_u32 v[208:209], s[10:11], v31, s22, v[4:5]
	s_add_i32 s10, s8, 12
	s_add_i32 s9, s7, 12
	v_or_b32_e32 v31, s9, v1
	v_or_b32_e32 v36, s10, v2
	v_or_b32_e32 v44, s10, v34
	v_or_b32_e32 v42, s9, v3
	v_ashrrev_i32_e32 v45, 31, v44
	v_ashrrev_i32_e32 v43, 31, v42
	v_lshlrev_b64 v[44:45], 12, v[44:45]
	v_lshlrev_b64 v[42:43], 12, v[42:43]
	v_lshl_add_u64 v[44:45], v[32:33], 0, v[44:45]
	v_lshl_add_u64 v[42:43], v[32:33], 0, v[42:43]
	global_load_dword v232, v[44:45], off
	global_load_dword v233, v[42:43], off
	v_mad_u64_u32 v[210:211], s[10:11], v36, s22, v[4:5]
	v_mad_u64_u32 v[212:213], s[10:11], v31, s22, v[4:5]
	s_add_i32 s10, s8, 16
	s_add_i32 s9, s7, 16
	v_or_b32_e32 v31, s9, v1
	v_or_b32_e32 v36, s10, v2
	v_or_b32_e32 v44, s10, v34
	v_or_b32_e32 v42, s9, v3
	v_ashrrev_i32_e32 v45, 31, v44
	v_ashrrev_i32_e32 v43, 31, v42
	v_lshlrev_b64 v[44:45], 12, v[44:45]
	v_lshlrev_b64 v[42:43], 12, v[42:43]
	v_lshl_add_u64 v[44:45], v[32:33], 0, v[44:45]
	v_lshl_add_u64 v[42:43], v[32:33], 0, v[42:43]
	global_load_dword v234, v[44:45], off
	global_load_dword v235, v[42:43], off
	v_mad_u64_u32 v[214:215], s[10:11], v36, s22, v[4:5]
	v_mad_u64_u32 v[216:217], s[10:11], v31, s22, v[4:5]
	s_add_i32 s10, s8, 20
	s_add_i32 s9, s7, 20
	v_or_b32_e32 v31, s9, v1
	v_or_b32_e32 v36, s10, v2
	v_or_b32_e32 v44, s10, v34
	v_or_b32_e32 v42, s9, v3
	v_ashrrev_i32_e32 v45, 31, v44
	v_ashrrev_i32_e32 v43, 31, v42
	v_lshlrev_b64 v[44:45], 12, v[44:45]
	v_lshlrev_b64 v[42:43], 12, v[42:43]
	v_lshl_add_u64 v[44:45], v[32:33], 0, v[44:45]
	v_lshl_add_u64 v[42:43], v[32:33], 0, v[42:43]
	global_load_dword v240, v[44:45], off
	global_load_dword v241, v[42:43], off
	v_mad_u64_u32 v[218:219], s[10:11], v36, s22, v[4:5]
	v_mad_u64_u32 v[220:221], s[10:11], v31, s22, v[4:5]
	s_add_i32 s10, s8, 24
	s_add_i32 s9, s7, 24
	v_or_b32_e32 v31, s9, v1
	v_or_b32_e32 v36, s10, v2
	s_add_i32 s8, s8, 28
	s_add_i32 s7, s7, 28
	s_cmp_lg_u32 s6, 0
	v_or_b32_e32 v44, s10, v34
	v_or_b32_e32 v42, s9, v3
	v_ashrrev_i32_e32 v45, 31, v44
	v_ashrrev_i32_e32 v43, 31, v42
	v_lshlrev_b64 v[44:45], 12, v[44:45]
	v_lshlrev_b64 v[42:43], 12, v[42:43]
	v_lshl_add_u64 v[44:45], v[32:33], 0, v[44:45]
	v_lshl_add_u64 v[42:43], v[32:33], 0, v[42:43]
	global_load_dword v242, v[44:45], off
	global_load_dword v243, v[42:43], off
	v_mad_u64_u32 v[222:223], s[10:11], v36, s22, v[4:5]
	v_mad_u64_u32 v[224:225], s[10:11], v31, s22, v[4:5]
	v_or_b32_e32 v36, s8, v2
	v_or_b32_e32 v31, s7, v1
	v_or_b32_e32 v44, s8, v34
	v_or_b32_e32 v42, s7, v3
	v_ashrrev_i32_e32 v45, 31, v44
	v_ashrrev_i32_e32 v43, 31, v42
	v_lshlrev_b64 v[44:45], 12, v[44:45]
	v_lshlrev_b64 v[42:43], 12, v[42:43]
	v_lshl_add_u64 v[44:45], v[32:33], 0, v[44:45]
	v_lshl_add_u64 v[42:43], v[32:33], 0, v[42:43]
	global_load_dword v41, v[44:45], off
	global_load_dword v46, v[42:43], off
	v_mad_u64_u32 v[42:43], s[8:9], v36, s22, v[4:5]
	v_mad_u64_u32 v[44:45], s[8:9], v31, s22, v[4:5]
	s_waitcnt vmcnt(14)
	ds_write_b32 v196, v226
	ds_write_b32 v198, v227
	s_waitcnt vmcnt(12)
	ds_write_b32 v200, v228
	ds_write_b32 v202, v229
	s_waitcnt vmcnt(10)
	ds_write_b32 v206, v230
	ds_write_b32 v208, v231
	s_waitcnt vmcnt(8)
	ds_write_b32 v210, v232
	ds_write_b32 v212, v233
	s_waitcnt vmcnt(6)
	ds_write_b32 v214, v234
	ds_write_b32 v216, v235
	s_waitcnt vmcnt(4)
	ds_write_b32 v218, v240
	ds_write_b32 v220, v241
	s_waitcnt vmcnt(2)
	ds_write_b32 v222, v242
	ds_write_b32 v224, v243
	s_waitcnt vmcnt(0)
	ds_write_b32 v42, v41
	ds_write_b32 v44, v46
	s_cbranch_scc1 .LBB0_154
	s_waitcnt lgkmcnt(0)
	ds_read2_b32 v[44:45], v37 offset0:33 offset1:41
	ds_read2_b32 v[46:47], v37 offset1:8
	ds_read2_b32 v[48:49], v37 offset0:66 offset1:74
	ds_read2_b32 v[50:51], v37 offset0:99 offset1:107
	ds_read2_b32 v[52:53], v37 offset0:132 offset1:140
	ds_read2_b32 v[54:55], v37 offset0:165 offset1:173
	ds_read2_b32 v[56:57], v37 offset0:198 offset1:206
	ds_read2_b32 v[58:59], v37 offset0:231 offset1:239
	v_mov_b32_e32 v31, v161
	v_or_b32_e32 v3, v35, v5
	v_lshl_add_u64 v[42:43], v[30:31], 1, v[14:15]
	v_lshlrev_b32_e32 v160, 11, v3
	v_or_b32_e32 v3, v35, v38
	s_waitcnt lgkmcnt(0)
	v_cvt_pk_bf16_f32 v30, v46, v44
	v_cvt_pk_bf16_f32 v31, v48, v50
	v_cvt_pk_bf16_f32 v32, v52, v54
	v_cvt_pk_bf16_f32 v33, v56, v58
	v_lshl_add_u64 v[60:61], v[42:43], 0, v[160:161]
	v_lshlrev_b32_e32 v160, 11, v3
	global_store_dwordx4 v[60:61], v[30:33], off
	v_or_b32_e32 v3, v35, v39
	s_nop 0
	v_cvt_pk_bf16_f32 v30, v47, v45
	v_cvt_pk_bf16_f32 v31, v49, v51
	v_cvt_pk_bf16_f32 v32, v53, v55
	v_cvt_pk_bf16_f32 v33, v57, v59
	v_lshl_add_u64 v[44:45], v[42:43], 0, v[160:161]
	global_store_dwordx4 v[44:45], v[30:33], off
	ds_read2_b32 v[44:45], v37 offset0:49 offset1:57
	ds_read2_b32 v[46:47], v37 offset0:16 offset1:24
	ds_read2_b32 v[48:49], v37 offset0:82 offset1:90
	ds_read2_b32 v[50:51], v37 offset0:115 offset1:123
	ds_read2_b32 v[52:53], v37 offset0:148 offset1:156
	ds_read2_b32 v[54:55], v37 offset0:181 offset1:189
	ds_read2_b32 v[56:57], v37 offset0:214 offset1:222
	ds_read2_b32 v[58:59], v37 offset0:247 offset1:255
	v_lshlrev_b32_e32 v160, 11, v3
	v_or_b32_e32 v3, v35, v40
	s_waitcnt lgkmcnt(6)
	v_cvt_pk_bf16_f32 v30, v46, v44
	s_waitcnt lgkmcnt(4)
	v_cvt_pk_bf16_f32 v31, v48, v50
	s_waitcnt lgkmcnt(2)
	v_cvt_pk_bf16_f32 v32, v52, v54
	s_waitcnt lgkmcnt(0)
	v_cvt_pk_bf16_f32 v33, v56, v58
	v_lshl_add_u64 v[60:61], v[42:43], 0, v[160:161]
	v_lshlrev_b32_e32 v160, 11, v3
	global_store_dwordx4 v[60:61], v[30:33], off
	v_lshl_add_u64 v[34:35], v[42:43], 0, v[160:161]
	s_nop 0
	v_cvt_pk_bf16_f32 v30, v47, v45
	v_cvt_pk_bf16_f32 v31, v49, v51
	v_cvt_pk_bf16_f32 v32, v53, v55
	v_cvt_pk_bf16_f32 v33, v57, v59
	global_store_dwordx4 v[34:35], v[30:33], off
	s_waitcnt lgkmcnt(0)

.LBB0_159:
	s_lshl_b32 s8, s5, 1
	s_lshl_b32 s7, s4, 1
	v_or_b32_e32 v42, s8, v36
	v_or_b32_e32 v41, s7, v3
	v_mad_i64_i32 v[42:43], s[10:11], v42, s24, v[34:35]
	v_mad_i64_i32 v[44:45], s[10:11], v41, s24, v[34:35]
	global_load_dword v226, v[42:43], off
	global_load_dword v227, v[44:45], off
	v_or_b32_e32 v31, s7, v1
	v_or_b32_e32 v33, s8, v2
	v_mad_u64_u32 v[196:197], s[10:11], v33, s22, v[4:5]
	v_mad_u64_u32 v[198:199], s[10:11], v31, s22, v[4:5]
	s_add_i32 s10, s8, 4
	s_add_i32 s9, s7, 4
	v_or_b32_e32 v33, s10, v2
	v_or_b32_e32 v31, s9, v1
	s_add_i32 s5, s5, 16
	s_add_i32 s4, s4, 16
	s_add_i32 s6, s6, -16
	v_or_b32_e32 v42, s10, v36
	v_or_b32_e32 v41, s9, v3
	v_mad_i64_i32 v[42:43], s[10:11], v42, s24, v[34:35]
	v_mad_i64_i32 v[44:45], s[10:11], v41, s24, v[34:35]
	global_load_dword v228, v[42:43], off
	global_load_dword v229, v[44:45], off
	v_mad_u64_u32 v[200:201], s[10:11], v33, s22, v[4:5]
	v_mad_u64_u32 v[202:203], s[10:11], v31, s22, v[4:5]
	s_add_i32 s10, s8, 8
	s_add_i32 s9, s7, 8
	v_or_b32_e32 v33, s10, v2
	v_or_b32_e32 v31, s9, v1
	v_or_b32_e32 v42, s10, v36
	v_or_b32_e32 v41, s9, v3
	v_mad_i64_i32 v[42:43], s[10:11], v42, s24, v[34:35]
	v_mad_i64_i32 v[44:45], s[10:11], v41, s24, v[34:35]
	global_load_dword v230, v[42:43], off
	global_load_dword v231, v[44:45], off
	v_mad_u64_u32 v[206:207], s[10:11], v33, s22, v[4:5]
	v_mad_u64_u32 v[208:209], s[10:11], v31, s22, v[4:5]
	s_add_i32 s10, s8, 12
	s_add_i32 s9, s7, 12
	v_or_b32_e32 v33, s10, v2
	v_or_b32_e32 v31, s9, v1
	v_or_b32_e32 v42, s10, v36
	v_or_b32_e32 v41, s9, v3
	v_mad_i64_i32 v[42:43], s[10:11], v42, s24, v[34:35]
	v_mad_i64_i32 v[44:45], s[10:11], v41, s24, v[34:35]
	global_load_dword v232, v[42:43], off
	global_load_dword v233, v[44:45], off
	v_mad_u64_u32 v[210:211], s[10:11], v33, s22, v[4:5]
	v_mad_u64_u32 v[212:213], s[10:11], v31, s22, v[4:5]
	s_add_i32 s10, s8, 16
	s_add_i32 s9, s7, 16
	v_or_b32_e32 v33, s10, v2
	v_or_b32_e32 v31, s9, v1
	v_or_b32_e32 v42, s10, v36
	v_or_b32_e32 v41, s9, v3
	v_mad_i64_i32 v[42:43], s[10:11], v42, s24, v[34:35]
	v_mad_i64_i32 v[44:45], s[10:11], v41, s24, v[34:35]
	global_load_dword v234, v[42:43], off
	global_load_dword v235, v[44:45], off
	v_mad_u64_u32 v[214:215], s[10:11], v33, s22, v[4:5]
	v_mad_u64_u32 v[216:217], s[10:11], v31, s22, v[4:5]
	s_add_i32 s10, s8, 20
	s_add_i32 s9, s7, 20
	v_or_b32_e32 v33, s10, v2
	v_or_b32_e32 v31, s9, v1
	v_or_b32_e32 v42, s10, v36
	v_or_b32_e32 v41, s9, v3
	v_mad_i64_i32 v[42:43], s[10:11], v42, s24, v[34:35]
	v_mad_i64_i32 v[44:45], s[10:11], v41, s24, v[34:35]
	global_load_dword v240, v[42:43], off
	global_load_dword v241, v[44:45], off
	v_mad_u64_u32 v[218:219], s[10:11], v33, s22, v[4:5]
	v_mad_u64_u32 v[220:221], s[10:11], v31, s22, v[4:5]
	s_add_i32 s10, s8, 24
	s_add_i32 s9, s7, 24
	v_or_b32_e32 v33, s10, v2
	v_or_b32_e32 v31, s9, v1
	s_add_i32 s8, s8, 28
	s_add_i32 s7, s7, 28
	s_cmp_lg_u32 s6, 0
	v_or_b32_e32 v42, s10, v36
	v_or_b32_e32 v41, s9, v3
	v_mad_i64_i32 v[42:43], s[10:11], v42, s24, v[34:35]
	v_mad_i64_i32 v[44:45], s[10:11], v41, s24, v[34:35]
	global_load_dword v242, v[42:43], off
	global_load_dword v243, v[44:45], off
	v_mad_u64_u32 v[222:223], s[10:11], v33, s22, v[4:5]
	v_mad_u64_u32 v[224:225], s[10:11], v31, s22, v[4:5]
	v_or_b32_e32 v33, s8, v2
	v_or_b32_e32 v31, s7, v1
	v_or_b32_e32 v42, s8, v36
	v_or_b32_e32 v41, s7, v3
	v_mad_i64_i32 v[42:43], s[8:9], v42, s24, v[34:35]
	v_mad_i64_i32 v[44:45], s[8:9], v41, s24, v[34:35]
	global_load_dword v41, v[42:43], off
	global_load_dword v46, v[44:45], off
	v_mad_u64_u32 v[42:43], s[8:9], v33, s22, v[4:5]
	v_mad_u64_u32 v[44:45], s[8:9], v31, s22, v[4:5]
	s_waitcnt vmcnt(14)
	ds_write_b32 v196, v226
	ds_write_b32 v198, v227
	s_waitcnt vmcnt(12)
	ds_write_b32 v200, v228
	ds_write_b32 v202, v229
	s_waitcnt vmcnt(10)
	ds_write_b32 v206, v230
	ds_write_b32 v208, v231
	s_waitcnt vmcnt(8)
	ds_write_b32 v210, v232
	ds_write_b32 v212, v233
	s_waitcnt vmcnt(6)
	ds_write_b32 v214, v234
	ds_write_b32 v216, v235
	s_waitcnt vmcnt(4)
	ds_write_b32 v218, v240
	ds_write_b32 v220, v241
	s_waitcnt vmcnt(2)
	ds_write_b32 v222, v242
	ds_write_b32 v224, v243
	s_waitcnt vmcnt(0)
	ds_write_b32 v42, v41
	ds_write_b32 v44, v46
	s_cbranch_scc1 .LBB0_159
	s_waitcnt lgkmcnt(0)
	ds_read2_b32 v[44:45], v37 offset0:33 offset1:41
	ds_read2_b32 v[46:47], v37 offset1:8
	ds_read2_b32 v[48:49], v37 offset0:66 offset1:74
	ds_read2_b32 v[50:51], v37 offset0:99 offset1:107
	ds_read2_b32 v[52:53], v37 offset0:132 offset1:140
	ds_read2_b32 v[54:55], v37 offset0:165 offset1:173
	ds_read2_b32 v[56:57], v37 offset0:198 offset1:206
	ds_read2_b32 v[58:59], v37 offset0:231 offset1:239
	v_or_b32_e32 v60, v30, v5
	v_ashrrev_i32_e32 v33, 31, v32
	v_ashrrev_i32_e32 v61, 31, v60
	v_lshl_add_u64 v[42:43], v[32:33], 1, v[16:17]
	v_lshlrev_b64 v[60:61], 11, v[60:61]
	s_waitcnt lgkmcnt(0)
	v_cvt_pk_bf16_f32 v32, v46, v44
	v_cvt_pk_bf16_f32 v33, v48, v50
	v_cvt_pk_bf16_f32 v34, v52, v54
	v_cvt_pk_bf16_f32 v35, v56, v58
	v_lshl_add_u64 v[60:61], v[42:43], 0, v[60:61]
	v_or_b32_e32 v44, v30, v38
	global_store_dwordx4 v[60:61], v[32:35], off
	v_or_b32_e32 v60, v30, v39
	v_ashrrev_i32_e32 v61, 31, v60
	v_cvt_pk_bf16_f32 v32, v47, v45
	v_ashrrev_i32_e32 v45, 31, v44
	v_lshlrev_b64 v[44:45], 11, v[44:45]
	v_cvt_pk_bf16_f32 v33, v49, v51
	v_cvt_pk_bf16_f32 v34, v53, v55
	v_cvt_pk_bf16_f32 v35, v57, v59
	v_lshl_add_u64 v[44:45], v[42:43], 0, v[44:45]
	global_store_dwordx4 v[44:45], v[32:35], off
	ds_read2_b32 v[44:45], v37 offset0:49 offset1:57
	ds_read2_b32 v[46:47], v37 offset0:16 offset1:24
	ds_read2_b32 v[48:49], v37 offset0:82 offset1:90
	ds_read2_b32 v[50:51], v37 offset0:115 offset1:123
	ds_read2_b32 v[52:53], v37 offset0:148 offset1:156
	ds_read2_b32 v[54:55], v37 offset0:181 offset1:189
	ds_read2_b32 v[56:57], v37 offset0:214 offset1:222
	ds_read2_b32 v[58:59], v37 offset0:247 offset1:255
	v_lshlrev_b64 v[60:61], 11, v[60:61]
	s_waitcnt lgkmcnt(6)
	v_cvt_pk_bf16_f32 v32, v46, v44
	s_waitcnt lgkmcnt(4)
	v_cvt_pk_bf16_f32 v33, v48, v50
	s_waitcnt lgkmcnt(2)
	v_cvt_pk_bf16_f32 v34, v52, v54
	s_waitcnt lgkmcnt(0)
	v_cvt_pk_bf16_f32 v35, v56, v58
	v_lshl_add_u64 v[60:61], v[42:43], 0, v[60:61]
	global_store_dwordx4 v[60:61], v[32:35], off
	v_cvt_pk_bf16_f32 v31, v49, v51
	s_nop 0
	v_or_b32_e32 v34, v30, v40
	v_ashrrev_i32_e32 v35, 31, v34
	v_lshlrev_b64 v[34:35], 11, v[34:35]
	v_cvt_pk_bf16_f32 v30, v47, v45
	v_cvt_pk_bf16_f32 v32, v53, v55
	v_cvt_pk_bf16_f32 v33, v57, v59
	v_lshl_add_u64 v[34:35], v[42:43], 0, v[34:35]
	global_store_dwordx4 v[34:35], v[30:33], off
	s_waitcnt lgkmcnt(0)
	s_branch .LBB0_128

.LBB0_308:
	s_lshl_b32 s8, s5, 1
	s_lshl_b32 s7, s4, 1
	v_or_b32_e32 v44, s8, v32
	v_or_b32_e32 v42, s7, v3
	v_ashrrev_i32_e32 v45, 31, v44
	v_ashrrev_i32_e32 v43, 31, v42
	v_lshlrev_b64 v[44:45], 12, v[44:45]
	v_lshlrev_b64 v[42:43], 12, v[42:43]
	v_lshl_add_u64 v[44:45], v[30:31], 0, v[44:45]
	v_lshl_add_u64 v[42:43], v[30:31], 0, v[42:43]
	global_load_dword v226, v[44:45], off
	global_load_dword v227, v[42:43], off
	v_or_b32_e32 v29, s7, v1
	v_or_b32_e32 v34, s8, v0
	v_mad_u64_u32 v[196:197], s[10:11], v34, s22, v[2:3]
	v_mad_u64_u32 v[198:199], s[10:11], v29, s22, v[2:3]
	s_add_i32 s10, s8, 4
	s_add_i32 s9, s7, 4
	v_or_b32_e32 v29, s9, v1
	v_or_b32_e32 v34, s10, v0
	s_add_i32 s5, s5, 16
	s_add_i32 s4, s4, 16
	s_add_i32 s6, s6, -16
	v_or_b32_e32 v44, s10, v32
	v_or_b32_e32 v42, s9, v3
	v_ashrrev_i32_e32 v45, 31, v44
	v_ashrrev_i32_e32 v43, 31, v42
	v_lshlrev_b64 v[44:45], 12, v[44:45]
	v_lshlrev_b64 v[42:43], 12, v[42:43]
	v_lshl_add_u64 v[44:45], v[30:31], 0, v[44:45]
	v_lshl_add_u64 v[42:43], v[30:31], 0, v[42:43]
	global_load_dword v228, v[44:45], off
	global_load_dword v229, v[42:43], off
	v_mad_u64_u32 v[200:201], s[10:11], v34, s22, v[2:3]
	v_mad_u64_u32 v[202:203], s[10:11], v29, s22, v[2:3]
	s_add_i32 s10, s8, 8
	s_add_i32 s9, s7, 8
	v_or_b32_e32 v29, s9, v1
	v_or_b32_e32 v34, s10, v0
	v_or_b32_e32 v44, s10, v32
	v_or_b32_e32 v42, s9, v3
	v_ashrrev_i32_e32 v45, 31, v44
	v_ashrrev_i32_e32 v43, 31, v42
	v_lshlrev_b64 v[44:45], 12, v[44:45]
	v_lshlrev_b64 v[42:43], 12, v[42:43]
	v_lshl_add_u64 v[44:45], v[30:31], 0, v[44:45]
	v_lshl_add_u64 v[42:43], v[30:31], 0, v[42:43]
	global_load_dword v230, v[44:45], off
	global_load_dword v231, v[42:43], off
	v_mad_u64_u32 v[206:207], s[10:11], v34, s22, v[2:3]
	v_mad_u64_u32 v[208:209], s[10:11], v29, s22, v[2:3]
	s_add_i32 s10, s8, 12
	s_add_i32 s9, s7, 12
	v_or_b32_e32 v29, s9, v1
	v_or_b32_e32 v34, s10, v0
	v_or_b32_e32 v44, s10, v32
	v_or_b32_e32 v42, s9, v3
	v_ashrrev_i32_e32 v45, 31, v44
	v_ashrrev_i32_e32 v43, 31, v42
	v_lshlrev_b64 v[44:45], 12, v[44:45]
	v_lshlrev_b64 v[42:43], 12, v[42:43]
	v_lshl_add_u64 v[44:45], v[30:31], 0, v[44:45]
	v_lshl_add_u64 v[42:43], v[30:31], 0, v[42:43]
	global_load_dword v232, v[44:45], off
	global_load_dword v233, v[42:43], off
	v_mad_u64_u32 v[210:211], s[10:11], v34, s22, v[2:3]
	v_mad_u64_u32 v[212:213], s[10:11], v29, s22, v[2:3]
	s_add_i32 s10, s8, 16
	s_add_i32 s9, s7, 16
	v_or_b32_e32 v29, s9, v1
	v_or_b32_e32 v34, s10, v0
	v_or_b32_e32 v44, s10, v32
	v_or_b32_e32 v42, s9, v3
	v_ashrrev_i32_e32 v45, 31, v44
	v_ashrrev_i32_e32 v43, 31, v42
	v_lshlrev_b64 v[44:45], 12, v[44:45]
	v_lshlrev_b64 v[42:43], 12, v[42:43]
	v_lshl_add_u64 v[44:45], v[30:31], 0, v[44:45]
	v_lshl_add_u64 v[42:43], v[30:31], 0, v[42:43]
	global_load_dword v234, v[44:45], off
	global_load_dword v235, v[42:43], off
	v_mad_u64_u32 v[214:215], s[10:11], v34, s22, v[2:3]
	v_mad_u64_u32 v[216:217], s[10:11], v29, s22, v[2:3]
	s_add_i32 s10, s8, 20
	s_add_i32 s9, s7, 20
	v_or_b32_e32 v29, s9, v1
	v_or_b32_e32 v34, s10, v0
	v_or_b32_e32 v44, s10, v32
	v_or_b32_e32 v42, s9, v3
	v_ashrrev_i32_e32 v45, 31, v44
	v_ashrrev_i32_e32 v43, 31, v42
	v_lshlrev_b64 v[44:45], 12, v[44:45]
	v_lshlrev_b64 v[42:43], 12, v[42:43]
	v_lshl_add_u64 v[44:45], v[30:31], 0, v[44:45]
	v_lshl_add_u64 v[42:43], v[30:31], 0, v[42:43]
	global_load_dword v240, v[44:45], off
	global_load_dword v241, v[42:43], off
	v_mad_u64_u32 v[218:219], s[10:11], v34, s22, v[2:3]
	v_mad_u64_u32 v[220:221], s[10:11], v29, s22, v[2:3]
	s_add_i32 s10, s8, 24
	s_add_i32 s9, s7, 24
	v_or_b32_e32 v29, s9, v1
	v_or_b32_e32 v34, s10, v0
	s_add_i32 s8, s8, 28
	s_add_i32 s7, s7, 28
	s_cmp_lg_u32 s6, 0
	v_or_b32_e32 v44, s10, v32
	v_or_b32_e32 v42, s9, v3
	v_ashrrev_i32_e32 v45, 31, v44
	v_ashrrev_i32_e32 v43, 31, v42
	v_lshlrev_b64 v[44:45], 12, v[44:45]
	v_lshlrev_b64 v[42:43], 12, v[42:43]
	v_lshl_add_u64 v[44:45], v[30:31], 0, v[44:45]
	v_lshl_add_u64 v[42:43], v[30:31], 0, v[42:43]
	global_load_dword v242, v[44:45], off
	global_load_dword v243, v[42:43], off
	v_mad_u64_u32 v[222:223], s[10:11], v34, s22, v[2:3]
	v_mad_u64_u32 v[224:225], s[10:11], v29, s22, v[2:3]
	v_or_b32_e32 v34, s8, v0
	v_or_b32_e32 v29, s7, v1
	v_or_b32_e32 v44, s8, v32
	v_or_b32_e32 v42, s7, v3
	v_ashrrev_i32_e32 v45, 31, v44
	v_ashrrev_i32_e32 v43, 31, v42
	v_lshlrev_b64 v[44:45], 12, v[44:45]
	v_lshlrev_b64 v[42:43], 12, v[42:43]
	v_lshl_add_u64 v[44:45], v[30:31], 0, v[44:45]
	v_lshl_add_u64 v[42:43], v[30:31], 0, v[42:43]
	global_load_dword v41, v[44:45], off
	global_load_dword v46, v[42:43], off
	v_mad_u64_u32 v[42:43], s[8:9], v34, s22, v[2:3]
	v_mad_u64_u32 v[44:45], s[8:9], v29, s22, v[2:3]
	s_waitcnt vmcnt(14)
	ds_write_b32 v196, v226
	ds_write_b32 v198, v227
	s_waitcnt vmcnt(12)
	ds_write_b32 v200, v228
	ds_write_b32 v202, v229
	s_waitcnt vmcnt(10)
	ds_write_b32 v206, v230
	ds_write_b32 v208, v231
	s_waitcnt vmcnt(8)
	ds_write_b32 v210, v232
	ds_write_b32 v212, v233
	s_waitcnt vmcnt(6)
	ds_write_b32 v214, v234
	ds_write_b32 v216, v235
	s_waitcnt vmcnt(4)
	ds_write_b32 v218, v240
	ds_write_b32 v220, v241
	s_waitcnt vmcnt(2)
	ds_write_b32 v222, v242
	ds_write_b32 v224, v243
	s_waitcnt vmcnt(0)
	ds_write_b32 v42, v41
	ds_write_b32 v44, v46
	s_cbranch_scc1 .LBB0_308
	s_waitcnt lgkmcnt(0)
	ds_read2_b32 v[44:45], v37 offset0:33 offset1:41
	ds_read2_b32 v[46:47], v37 offset1:8
	ds_read2_b32 v[48:49], v37 offset0:66 offset1:74
	ds_read2_b32 v[50:51], v37 offset0:99 offset1:107
	ds_read2_b32 v[52:53], v37 offset0:132 offset1:140
	ds_read2_b32 v[54:55], v37 offset0:165 offset1:173
	ds_read2_b32 v[56:57], v37 offset0:198 offset1:206
	ds_read2_b32 v[58:59], v37 offset0:231 offset1:239
	v_or_b32_e32 v3, v33, v36
	v_mul_u32_u24_e32 v3, 0xb00, v3
	v_mov_b32_e32 v29, v161
	v_lshlrev_b32_e32 v160, 1, v3
	v_or_b32_e32 v3, v33, v38
	v_lshl_add_u64 v[42:43], v[28:29], 1, v[4:5]
	v_mul_u32_u24_e32 v3, 0xb00, v3
	s_waitcnt lgkmcnt(0)
	v_cvt_pk_bf16_f32 v28, v46, v44
	v_cvt_pk_bf16_f32 v29, v48, v50
	v_cvt_pk_bf16_f32 v30, v52, v54
	v_cvt_pk_bf16_f32 v31, v56, v58
	v_lshl_add_u64 v[60:61], v[42:43], 0, v[160:161]
	v_lshlrev_b32_e32 v160, 1, v3
	global_store_dwordx4 v[60:61], v[28:31], off
	v_or_b32_e32 v3, v33, v39
	v_mul_u32_u24_e32 v3, 0xb00, v3
	v_cvt_pk_bf16_f32 v28, v47, v45
	v_cvt_pk_bf16_f32 v29, v49, v51
	v_cvt_pk_bf16_f32 v30, v53, v55
	v_cvt_pk_bf16_f32 v31, v57, v59
	v_lshl_add_u64 v[44:45], v[42:43], 0, v[160:161]
	global_store_dwordx4 v[44:45], v[28:31], off
	ds_read2_b32 v[44:45], v37 offset0:16 offset1:24
	ds_read2_b32 v[46:47], v37 offset0:49 offset1:57
	ds_read2_b32 v[48:49], v37 offset0:82 offset1:90
	ds_read2_b32 v[50:51], v37 offset0:115 offset1:123
	ds_read2_b32 v[52:53], v37 offset0:148 offset1:156
	ds_read2_b32 v[54:55], v37 offset0:181 offset1:189
	ds_read2_b32 v[56:57], v37 offset0:214 offset1:222
	ds_read2_b32 v[58:59], v37 offset0:247 offset1:255
	v_lshlrev_b32_e32 v160, 1, v3
	v_or_b32_e32 v3, v33, v40
	v_mul_u32_u24_e32 v3, 0xb00, v3
	s_waitcnt lgkmcnt(6)
	v_cvt_pk_bf16_f32 v28, v44, v46
	s_waitcnt lgkmcnt(4)
	v_cvt_pk_bf16_f32 v29, v48, v50
	s_waitcnt lgkmcnt(2)
	v_cvt_pk_bf16_f32 v30, v52, v54
	s_waitcnt lgkmcnt(0)
	v_cvt_pk_bf16_f32 v31, v56, v58
	v_lshl_add_u64 v[60:61], v[42:43], 0, v[160:161]
	v_lshlrev_b32_e32 v160, 1, v3
	global_store_dwordx4 v[60:61], v[28:31], off
	v_lshl_add_u64 v[32:33], v[42:43], 0, v[160:161]
	s_nop 0
	v_cvt_pk_bf16_f32 v28, v45, v47
	v_cvt_pk_bf16_f32 v29, v49, v51
	v_cvt_pk_bf16_f32 v30, v53, v55
	v_cvt_pk_bf16_f32 v31, v57, v59
	global_store_dwordx4 v[32:33], v[28:31], off
	s_waitcnt lgkmcnt(0)

.LBB0_312:
	s_lshl_b32 s10, s7, 1
	s_lshl_b32 s9, s6, 1
	v_or_b32_e32 v42, s10, v30
	v_or_b32_e32 v44, s9, v3
	v_mad_u64_u32 v[42:43], s[12:13], v42, s23, v[28:29]
	v_mad_u64_u32 v[44:45], s[12:13], v44, s23, v[28:29]
	global_load_dword v226, v[42:43], off
	global_load_dword v227, v[44:45], off
	v_or_b32_e32 v34, s9, v1
	v_or_b32_e32 v41, s10, v0
	v_mad_u64_u32 v[196:197], s[12:13], v41, s22, v[2:3]
	v_mad_u64_u32 v[198:199], s[12:13], v34, s22, v[2:3]
	s_add_i32 s12, s10, 4
	s_add_i32 s11, s9, 4
	v_or_b32_e32 v41, s12, v0
	v_or_b32_e32 v34, s11, v1
	s_add_i32 s7, s7, 16
	s_add_i32 s6, s6, 16
	s_add_i32 s8, s8, -16
	v_or_b32_e32 v42, s12, v30
	v_or_b32_e32 v44, s11, v3
	v_mad_u64_u32 v[42:43], s[12:13], v42, s23, v[28:29]
	v_mad_u64_u32 v[44:45], s[12:13], v44, s23, v[28:29]
	global_load_dword v228, v[42:43], off
	global_load_dword v229, v[44:45], off
	v_mad_u64_u32 v[200:201], s[12:13], v41, s22, v[2:3]
	v_mad_u64_u32 v[202:203], s[12:13], v34, s22, v[2:3]
	s_add_i32 s12, s10, 8
	s_add_i32 s11, s9, 8
	v_or_b32_e32 v41, s12, v0
	v_or_b32_e32 v34, s11, v1
	v_or_b32_e32 v42, s12, v30
	v_or_b32_e32 v44, s11, v3
	v_mad_u64_u32 v[42:43], s[12:13], v42, s23, v[28:29]
	v_mad_u64_u32 v[44:45], s[12:13], v44, s23, v[28:29]
	global_load_dword v230, v[42:43], off
	global_load_dword v231, v[44:45], off
	v_mad_u64_u32 v[206:207], s[12:13], v41, s22, v[2:3]
	v_mad_u64_u32 v[208:209], s[12:13], v34, s22, v[2:3]
	s_add_i32 s12, s10, 12
	s_add_i32 s11, s9, 12
	v_or_b32_e32 v41, s12, v0
	v_or_b32_e32 v34, s11, v1
	v_or_b32_e32 v42, s12, v30
	v_or_b32_e32 v44, s11, v3
	v_mad_u64_u32 v[42:43], s[12:13], v42, s23, v[28:29]
	v_mad_u64_u32 v[44:45], s[12:13], v44, s23, v[28:29]
	global_load_dword v232, v[42:43], off
	global_load_dword v233, v[44:45], off
	v_mad_u64_u32 v[210:211], s[12:13], v41, s22, v[2:3]
	v_mad_u64_u32 v[212:213], s[12:13], v34, s22, v[2:3]
	s_add_i32 s12, s10, 16
	s_add_i32 s11, s9, 16
	v_or_b32_e32 v41, s12, v0
	v_or_b32_e32 v34, s11, v1
	v_or_b32_e32 v42, s12, v30
	v_or_b32_e32 v44, s11, v3
	v_mad_u64_u32 v[42:43], s[12:13], v42, s23, v[28:29]
	v_mad_u64_u32 v[44:45], s[12:13], v44, s23, v[28:29]
	global_load_dword v234, v[42:43], off
	global_load_dword v235, v[44:45], off
	v_mad_u64_u32 v[214:215], s[12:13], v41, s22, v[2:3]
	v_mad_u64_u32 v[216:217], s[12:13], v34, s22, v[2:3]
	s_add_i32 s12, s10, 20
	s_add_i32 s11, s9, 20
	v_or_b32_e32 v41, s12, v0
	v_or_b32_e32 v34, s11, v1
	v_or_b32_e32 v42, s12, v30
	v_or_b32_e32 v44, s11, v3
	v_mad_u64_u32 v[42:43], s[12:13], v42, s23, v[28:29]
	v_mad_u64_u32 v[44:45], s[12:13], v44, s23, v[28:29]
	global_load_dword v240, v[42:43], off
	global_load_dword v241, v[44:45], off
	v_mad_u64_u32 v[218:219], s[12:13], v41, s22, v[2:3]
	v_mad_u64_u32 v[220:221], s[12:13], v34, s22, v[2:3]
	s_add_i32 s12, s10, 24
	s_add_i32 s11, s9, 24
	v_or_b32_e32 v41, s12, v0
	v_or_b32_e32 v34, s11, v1
	s_add_i32 s10, s10, 28
	s_add_i32 s9, s9, 28
	s_cmp_lg_u32 s8, 0
	v_or_b32_e32 v42, s12, v30
	v_or_b32_e32 v44, s11, v3
	v_mad_u64_u32 v[42:43], s[12:13], v42, s23, v[28:29]
	v_mad_u64_u32 v[44:45], s[12:13], v44, s23, v[28:29]
	global_load_dword v242, v[42:43], off
	global_load_dword v243, v[44:45], off
	v_mad_u64_u32 v[222:223], s[12:13], v41, s22, v[2:3]
	v_mad_u64_u32 v[224:225], s[12:13], v34, s22, v[2:3]
	v_or_b32_e32 v41, s10, v0
	v_or_b32_e32 v34, s9, v1
	v_or_b32_e32 v42, s10, v30
	v_or_b32_e32 v44, s9, v3
	v_mad_u64_u32 v[42:43], s[10:11], v42, s23, v[28:29]
	v_mad_u64_u32 v[44:45], s[10:11], v44, s23, v[28:29]
	global_load_dword v46, v[42:43], off
	global_load_dword v47, v[44:45], off
	v_mad_u64_u32 v[42:43], s[10:11], v41, s22, v[2:3]
	v_mad_u64_u32 v[44:45], s[10:11], v34, s22, v[2:3]
	s_waitcnt vmcnt(14)
	ds_write_b32 v196, v226
	ds_write_b32 v198, v227
	s_waitcnt vmcnt(12)
	ds_write_b32 v200, v228
	ds_write_b32 v202, v229
	s_waitcnt vmcnt(10)
	ds_write_b32 v206, v230
	ds_write_b32 v208, v231
	s_waitcnt vmcnt(8)
	ds_write_b32 v210, v232
	ds_write_b32 v212, v233
	s_waitcnt vmcnt(6)
	ds_write_b32 v214, v234
	ds_write_b32 v216, v235
	s_waitcnt vmcnt(4)
	ds_write_b32 v218, v240
	ds_write_b32 v220, v241
	s_waitcnt vmcnt(2)
	ds_write_b32 v222, v242
	ds_write_b32 v224, v243
	s_waitcnt vmcnt(0)
	ds_write_b32 v42, v46
	ds_write_b32 v44, v47
	s_cbranch_scc1 .LBB0_312
	s_waitcnt lgkmcnt(0)
	ds_read2_b32 v[28:29], v37 offset0:33 offset1:41
	ds_read2_b32 v[48:49], v37 offset1:8
	s_movk_i32 s6, 0x57
	v_cmp_lt_u16_e32 vcc, s6, v32
	v_mov_b32_e32 v3, 0xfffff500
	ds_read2_b32 v[50:51], v37 offset0:66 offset1:74
	ds_read2_b32 v[52:53], v37 offset0:99 offset1:107
	v_cndmask_b32_e32 v3, 0, v3, vcc
	s_waitcnt lgkmcnt(0)
	v_cvt_pk_bf16_f32 v42, v48, v28
	v_add_lshl_u32 v28, v3, v31, 1
	ds_read2_b32 v[54:55], v37 offset0:132 offset1:140
	ds_read2_b32 v[56:57], v37 offset0:165 offset1:173
	ds_read2_b32 v[58:59], v37 offset0:198 offset1:206
	ds_read2_b32 v[60:61], v37 offset0:231 offset1:239
	v_and_b32_e32 v28, 0xffffff00, v28
	v_mov_b32_e32 v30, 0x80
	s_movk_i32 s6, 0x60
	v_cndmask_b32_e32 v30, 0, v30, vcc
	v_and_or_b32 v28, v31, s6, v28
	v_or3_b32 v32, v28, v36, v30
	v_lshlrev_b32_e32 v160, 1, v33
	v_ashrrev_i32_e32 v33, 31, v32
	v_lshl_add_u64 v[46:47], v[6:7], 0, v[160:161]
	v_lshlrev_b64 v[32:33], 11, v[32:33]
	v_or_b32_e32 v28, v38, v31
	v_cvt_pk_bf16_f32 v43, v50, v52
	s_waitcnt lgkmcnt(2)
	v_cvt_pk_bf16_f32 v44, v54, v56
	s_waitcnt lgkmcnt(0)
	v_cvt_pk_bf16_f32 v45, v58, v60
	v_lshl_add_u64 v[32:33], v[46:47], 0, v[32:33]
	v_add_lshl_u32 v28, v28, v3, 1
	s_movk_i32 s6, 0x6f
	global_store_dwordx4 v[32:33], v[42:45], off
	v_and_b32_e32 v28, 0xffffff00, v28
	s_nop 0
	v_cvt_pk_bf16_f32 v42, v49, v29
	v_bitop3_b32 v29, v38, s6, v31 bitop3:0xc8
	v_or3_b32 v28, v29, v28, v30
	v_ashrrev_i32_e32 v29, 31, v28
	v_lshlrev_b64 v[28:29], 11, v[28:29]
	v_cvt_pk_bf16_f32 v43, v51, v53
	v_cvt_pk_bf16_f32 v44, v55, v57
	v_cvt_pk_bf16_f32 v45, v59, v61
	v_lshl_add_u64 v[28:29], v[46:47], 0, v[28:29]
	global_store_dwordx4 v[28:29], v[42:45], off
	ds_read2_b32 v[28:29], v37 offset0:49 offset1:57
	ds_read2_b32 v[32:33], v37 offset0:16 offset1:24
	s_movk_i32 s6, 0x77
	ds_read2_b32 v[48:49], v37 offset0:82 offset1:90
	ds_read2_b32 v[50:51], v37 offset0:115 offset1:123
	ds_read2_b32 v[52:53], v37 offset0:148 offset1:156
	ds_read2_b32 v[54:55], v37 offset0:181 offset1:189
	ds_read2_b32 v[56:57], v37 offset0:214 offset1:222
	ds_read2_b32 v[58:59], v37 offset0:247 offset1:255
	s_waitcnt lgkmcnt(6)
	v_cvt_pk_bf16_f32 v42, v32, v28
	v_or_b32_e32 v28, v39, v31
	v_add_lshl_u32 v28, v28, v3, 1
	v_and_b32_e32 v28, 0xffffff00, v28
	v_bitop3_b32 v32, v39, s6, v31 bitop3:0xc8
	v_or3_b32 v60, v32, v28, v30
	v_or_b32_e32 v28, v40, v31
	v_add_lshl_u32 v3, v28, v3, 1
	s_movk_i32 s6, 0x7f
	v_and_b32_e32 v3, 0xffffff00, v3
	v_bitop3_b32 v28, v40, s6, v31 bitop3:0xc8
	v_or3_b32 v32, v28, v3, v30
	v_ashrrev_i32_e32 v61, 31, v60
	v_cvt_pk_bf16_f32 v28, v33, v29
	v_ashrrev_i32_e32 v33, 31, v32
	v_lshlrev_b64 v[60:61], 11, v[60:61]
	v_lshlrev_b64 v[32:33], 11, v[32:33]
	s_waitcnt lgkmcnt(4)
	v_cvt_pk_bf16_f32 v43, v48, v50
	s_waitcnt lgkmcnt(2)
	v_cvt_pk_bf16_f32 v44, v52, v54
	s_waitcnt lgkmcnt(0)
	v_cvt_pk_bf16_f32 v45, v56, v58
	v_lshl_add_u64 v[60:61], v[46:47], 0, v[60:61]
	v_cvt_pk_bf16_f32 v29, v49, v51
	v_cvt_pk_bf16_f32 v30, v53, v55
	v_cvt_pk_bf16_f32 v31, v57, v59
	v_lshl_add_u64 v[32:33], v[46:47], 0, v[32:33]
	global_store_dwordx4 v[60:61], v[42:45], off
	global_store_dwordx4 v[32:33], v[28:31], off
	s_waitcnt lgkmcnt(0)

.LBB0_317:
	s_lshl_b32 s8, s5, 1
	s_lshl_b32 s7, s4, 1
	v_or_b32_e32 v44, s8, v32
	v_or_b32_e32 v42, s7, v3
	v_ashrrev_i32_e32 v45, 31, v44
	v_ashrrev_i32_e32 v43, 31, v42
	v_lshlrev_b64 v[44:45], 12, v[44:45]
	v_lshlrev_b64 v[42:43], 12, v[42:43]
	v_lshl_add_u64 v[44:45], v[30:31], 0, v[44:45]
	v_lshl_add_u64 v[42:43], v[30:31], 0, v[42:43]
	global_load_dword v226, v[44:45], off
	global_load_dword v227, v[42:43], off
	v_or_b32_e32 v29, s7, v1
	v_or_b32_e32 v34, s8, v0
	v_mad_u64_u32 v[196:197], s[10:11], v34, s22, v[2:3]
	v_mad_u64_u32 v[198:199], s[10:11], v29, s22, v[2:3]
	s_add_i32 s10, s8, 4
	s_add_i32 s9, s7, 4
	v_or_b32_e32 v29, s9, v1
	v_or_b32_e32 v34, s10, v0
	s_add_i32 s5, s5, 16
	s_add_i32 s4, s4, 16
	s_add_i32 s6, s6, -16
	v_or_b32_e32 v44, s10, v32
	v_or_b32_e32 v42, s9, v3
	v_ashrrev_i32_e32 v45, 31, v44
	v_ashrrev_i32_e32 v43, 31, v42
	v_lshlrev_b64 v[44:45], 12, v[44:45]
	v_lshlrev_b64 v[42:43], 12, v[42:43]
	v_lshl_add_u64 v[44:45], v[30:31], 0, v[44:45]
	v_lshl_add_u64 v[42:43], v[30:31], 0, v[42:43]
	global_load_dword v228, v[44:45], off
	global_load_dword v229, v[42:43], off
	v_mad_u64_u32 v[200:201], s[10:11], v34, s22, v[2:3]
	v_mad_u64_u32 v[202:203], s[10:11], v29, s22, v[2:3]
	s_add_i32 s10, s8, 8
	s_add_i32 s9, s7, 8
	v_or_b32_e32 v29, s9, v1
	v_or_b32_e32 v34, s10, v0
	v_or_b32_e32 v44, s10, v32
	v_or_b32_e32 v42, s9, v3
	v_ashrrev_i32_e32 v45, 31, v44
	v_ashrrev_i32_e32 v43, 31, v42
	v_lshlrev_b64 v[44:45], 12, v[44:45]
	v_lshlrev_b64 v[42:43], 12, v[42:43]
	v_lshl_add_u64 v[44:45], v[30:31], 0, v[44:45]
	v_lshl_add_u64 v[42:43], v[30:31], 0, v[42:43]
	global_load_dword v230, v[44:45], off
	global_load_dword v231, v[42:43], off
	v_mad_u64_u32 v[206:207], s[10:11], v34, s22, v[2:3]
	v_mad_u64_u32 v[208:209], s[10:11], v29, s22, v[2:3]
	s_add_i32 s10, s8, 12
	s_add_i32 s9, s7, 12
	v_or_b32_e32 v29, s9, v1
	v_or_b32_e32 v34, s10, v0
	v_or_b32_e32 v44, s10, v32
	v_or_b32_e32 v42, s9, v3
	v_ashrrev_i32_e32 v45, 31, v44
	v_ashrrev_i32_e32 v43, 31, v42
	v_lshlrev_b64 v[44:45], 12, v[44:45]
	v_lshlrev_b64 v[42:43], 12, v[42:43]
	v_lshl_add_u64 v[44:45], v[30:31], 0, v[44:45]
	v_lshl_add_u64 v[42:43], v[30:31], 0, v[42:43]
	global_load_dword v232, v[44:45], off
	global_load_dword v233, v[42:43], off
	v_mad_u64_u32 v[210:211], s[10:11], v34, s22, v[2:3]
	v_mad_u64_u32 v[212:213], s[10:11], v29, s22, v[2:3]
	s_add_i32 s10, s8, 16
	s_add_i32 s9, s7, 16
	v_or_b32_e32 v29, s9, v1
	v_or_b32_e32 v34, s10, v0
	v_or_b32_e32 v44, s10, v32
	v_or_b32_e32 v42, s9, v3
	v_ashrrev_i32_e32 v45, 31, v44
	v_ashrrev_i32_e32 v43, 31, v42
	v_lshlrev_b64 v[44:45], 12, v[44:45]
	v_lshlrev_b64 v[42:43], 12, v[42:43]
	v_lshl_add_u64 v[44:45], v[30:31], 0, v[44:45]
	v_lshl_add_u64 v[42:43], v[30:31], 0, v[42:43]
	global_load_dword v234, v[44:45], off
	global_load_dword v235, v[42:43], off
	v_mad_u64_u32 v[214:215], s[10:11], v34, s22, v[2:3]
	v_mad_u64_u32 v[216:217], s[10:11], v29, s22, v[2:3]
	s_add_i32 s10, s8, 20
	s_add_i32 s9, s7, 20
	v_or_b32_e32 v29, s9, v1
	v_or_b32_e32 v34, s10, v0
	v_or_b32_e32 v44, s10, v32
	v_or_b32_e32 v42, s9, v3
	v_ashrrev_i32_e32 v45, 31, v44
	v_ashrrev_i32_e32 v43, 31, v42
	v_lshlrev_b64 v[44:45], 12, v[44:45]
	v_lshlrev_b64 v[42:43], 12, v[42:43]
	v_lshl_add_u64 v[44:45], v[30:31], 0, v[44:45]
	v_lshl_add_u64 v[42:43], v[30:31], 0, v[42:43]
	global_load_dword v240, v[44:45], off
	global_load_dword v241, v[42:43], off
	v_mad_u64_u32 v[218:219], s[10:11], v34, s22, v[2:3]
	v_mad_u64_u32 v[220:221], s[10:11], v29, s22, v[2:3]
	s_add_i32 s10, s8, 24
	s_add_i32 s9, s7, 24
	v_or_b32_e32 v29, s9, v1
	v_or_b32_e32 v34, s10, v0
	s_add_i32 s8, s8, 28
	s_add_i32 s7, s7, 28
	s_cmp_lg_u32 s6, 0
	v_or_b32_e32 v44, s10, v32
	v_or_b32_e32 v42, s9, v3
	v_ashrrev_i32_e32 v45, 31, v44
	v_ashrrev_i32_e32 v43, 31, v42
	v_lshlrev_b64 v[44:45], 12, v[44:45]
	v_lshlrev_b64 v[42:43], 12, v[42:43]
	v_lshl_add_u64 v[44:45], v[30:31], 0, v[44:45]
	v_lshl_add_u64 v[42:43], v[30:31], 0, v[42:43]
	global_load_dword v242, v[44:45], off
	global_load_dword v243, v[42:43], off
	v_mad_u64_u32 v[222:223], s[10:11], v34, s22, v[2:3]
	v_mad_u64_u32 v[224:225], s[10:11], v29, s22, v[2:3]
	v_or_b32_e32 v34, s8, v0
	v_or_b32_e32 v29, s7, v1
	v_or_b32_e32 v44, s8, v32
	v_or_b32_e32 v42, s7, v3
	v_ashrrev_i32_e32 v45, 31, v44
	v_ashrrev_i32_e32 v43, 31, v42
	v_lshlrev_b64 v[44:45], 12, v[44:45]
	v_lshlrev_b64 v[42:43], 12, v[42:43]
	v_lshl_add_u64 v[44:45], v[30:31], 0, v[44:45]
	v_lshl_add_u64 v[42:43], v[30:31], 0, v[42:43]
	global_load_dword v41, v[44:45], off
	global_load_dword v46, v[42:43], off
	v_mad_u64_u32 v[42:43], s[8:9], v34, s22, v[2:3]
	v_mad_u64_u32 v[44:45], s[8:9], v29, s22, v[2:3]
	s_waitcnt vmcnt(14)
	ds_write_b32 v196, v226
	ds_write_b32 v198, v227
	s_waitcnt vmcnt(12)
	ds_write_b32 v200, v228
	ds_write_b32 v202, v229
	s_waitcnt vmcnt(10)
	ds_write_b32 v206, v230
	ds_write_b32 v208, v231
	s_waitcnt vmcnt(8)
	ds_write_b32 v210, v232
	ds_write_b32 v212, v233
	s_waitcnt vmcnt(6)
	ds_write_b32 v214, v234
	ds_write_b32 v216, v235
	s_waitcnt vmcnt(4)
	ds_write_b32 v218, v240
	ds_write_b32 v220, v241
	s_waitcnt vmcnt(2)
	ds_write_b32 v222, v242
	ds_write_b32 v224, v243
	s_waitcnt vmcnt(0)
	ds_write_b32 v42, v41
	ds_write_b32 v44, v46
	s_cbranch_scc1 .LBB0_317
	s_waitcnt lgkmcnt(0)
	ds_read2_b32 v[44:45], v37 offset0:33 offset1:41
	ds_read2_b32 v[46:47], v37 offset1:8
	ds_read2_b32 v[48:49], v37 offset0:66 offset1:74
	ds_read2_b32 v[50:51], v37 offset0:99 offset1:107
	ds_read2_b32 v[52:53], v37 offset0:132 offset1:140
	ds_read2_b32 v[54:55], v37 offset0:165 offset1:173
	ds_read2_b32 v[56:57], v37 offset0:198 offset1:206
	ds_read2_b32 v[58:59], v37 offset0:231 offset1:239
	v_mov_b32_e32 v29, v161
	v_or_b32_e32 v3, v33, v36
	v_lshl_add_u64 v[42:43], v[28:29], 1, v[8:9]
	v_lshlrev_b32_e32 v160, 11, v3
	v_or_b32_e32 v3, v33, v38
	s_waitcnt lgkmcnt(0)
	v_cvt_pk_bf16_f32 v28, v46, v44
	v_cvt_pk_bf16_f32 v29, v48, v50
	v_cvt_pk_bf16_f32 v30, v52, v54
	v_cvt_pk_bf16_f32 v31, v56, v58
	v_lshl_add_u64 v[60:61], v[42:43], 0, v[160:161]
	v_lshlrev_b32_e32 v160, 11, v3
	global_store_dwordx4 v[60:61], v[28:31], off
	v_or_b32_e32 v3, v33, v39
	s_nop 0
	v_cvt_pk_bf16_f32 v28, v47, v45
	v_cvt_pk_bf16_f32 v29, v49, v51
	v_cvt_pk_bf16_f32 v30, v53, v55
	v_cvt_pk_bf16_f32 v31, v57, v59
	v_lshl_add_u64 v[44:45], v[42:43], 0, v[160:161]
	global_store_dwordx4 v[44:45], v[28:31], off
	ds_read2_b32 v[44:45], v37 offset0:49 offset1:57
	ds_read2_b32 v[46:47], v37 offset0:16 offset1:24
	ds_read2_b32 v[48:49], v37 offset0:82 offset1:90
	ds_read2_b32 v[50:51], v37 offset0:115 offset1:123
	ds_read2_b32 v[52:53], v37 offset0:148 offset1:156
	ds_read2_b32 v[54:55], v37 offset0:181 offset1:189
	ds_read2_b32 v[56:57], v37 offset0:214 offset1:222
	ds_read2_b32 v[58:59], v37 offset0:247 offset1:255
	v_lshlrev_b32_e32 v160, 11, v3
	v_or_b32_e32 v3, v33, v40
	s_waitcnt lgkmcnt(6)
	v_cvt_pk_bf16_f32 v28, v46, v44
	s_waitcnt lgkmcnt(4)
	v_cvt_pk_bf16_f32 v29, v48, v50
	s_waitcnt lgkmcnt(2)
	v_cvt_pk_bf16_f32 v30, v52, v54
	s_waitcnt lgkmcnt(0)
	v_cvt_pk_bf16_f32 v31, v56, v58
	v_lshl_add_u64 v[60:61], v[42:43], 0, v[160:161]
	v_lshlrev_b32_e32 v160, 11, v3
	global_store_dwordx4 v[60:61], v[28:31], off
	v_lshl_add_u64 v[32:33], v[42:43], 0, v[160:161]
	s_nop 0
	v_cvt_pk_bf16_f32 v28, v47, v45
	v_cvt_pk_bf16_f32 v29, v49, v51
	v_cvt_pk_bf16_f32 v30, v53, v55
	v_cvt_pk_bf16_f32 v31, v57, v59
	global_store_dwordx4 v[32:33], v[28:31], off
	s_waitcnt lgkmcnt(0)

.LBB0_322:
	s_lshl_b32 s8, s5, 1
	s_lshl_b32 s7, s4, 1
	v_or_b32_e32 v44, s8, v32
	v_or_b32_e32 v42, s7, v3
	v_ashrrev_i32_e32 v45, 31, v44
	v_ashrrev_i32_e32 v43, 31, v42
	v_lshlrev_b64 v[44:45], 12, v[44:45]
	v_lshlrev_b64 v[42:43], 12, v[42:43]
	v_lshl_add_u64 v[44:45], v[30:31], 0, v[44:45]
	v_lshl_add_u64 v[42:43], v[30:31], 0, v[42:43]
	global_load_dword v226, v[44:45], off
	global_load_dword v227, v[42:43], off
	v_or_b32_e32 v29, s7, v1
	v_or_b32_e32 v34, s8, v0
	v_mad_u64_u32 v[196:197], s[10:11], v34, s22, v[2:3]
	v_mad_u64_u32 v[198:199], s[10:11], v29, s22, v[2:3]
	s_add_i32 s10, s8, 4
	s_add_i32 s9, s7, 4
	v_or_b32_e32 v29, s9, v1
	v_or_b32_e32 v34, s10, v0
	s_add_i32 s5, s5, 16
	s_add_i32 s4, s4, 16
	s_add_i32 s6, s6, -16
	v_or_b32_e32 v44, s10, v32
	v_or_b32_e32 v42, s9, v3
	v_ashrrev_i32_e32 v45, 31, v44
	v_ashrrev_i32_e32 v43, 31, v42
	v_lshlrev_b64 v[44:45], 12, v[44:45]
	v_lshlrev_b64 v[42:43], 12, v[42:43]
	v_lshl_add_u64 v[44:45], v[30:31], 0, v[44:45]
	v_lshl_add_u64 v[42:43], v[30:31], 0, v[42:43]
	global_load_dword v228, v[44:45], off
	global_load_dword v229, v[42:43], off
	v_mad_u64_u32 v[200:201], s[10:11], v34, s22, v[2:3]
	v_mad_u64_u32 v[202:203], s[10:11], v29, s22, v[2:3]
	s_add_i32 s10, s8, 8
	s_add_i32 s9, s7, 8
	v_or_b32_e32 v29, s9, v1
	v_or_b32_e32 v34, s10, v0
	v_or_b32_e32 v44, s10, v32
	v_or_b32_e32 v42, s9, v3
	v_ashrrev_i32_e32 v45, 31, v44
	v_ashrrev_i32_e32 v43, 31, v42
	v_lshlrev_b64 v[44:45], 12, v[44:45]
	v_lshlrev_b64 v[42:43], 12, v[42:43]
	v_lshl_add_u64 v[44:45], v[30:31], 0, v[44:45]
	v_lshl_add_u64 v[42:43], v[30:31], 0, v[42:43]
	global_load_dword v230, v[44:45], off
	global_load_dword v231, v[42:43], off
	v_mad_u64_u32 v[206:207], s[10:11], v34, s22, v[2:3]
	v_mad_u64_u32 v[208:209], s[10:11], v29, s22, v[2:3]
	s_add_i32 s10, s8, 12
	s_add_i32 s9, s7, 12
	v_or_b32_e32 v29, s9, v1
	v_or_b32_e32 v34, s10, v0
	v_or_b32_e32 v44, s10, v32
	v_or_b32_e32 v42, s9, v3
	v_ashrrev_i32_e32 v45, 31, v44
	v_ashrrev_i32_e32 v43, 31, v42
	v_lshlrev_b64 v[44:45], 12, v[44:45]
	v_lshlrev_b64 v[42:43], 12, v[42:43]
	v_lshl_add_u64 v[44:45], v[30:31], 0, v[44:45]
	v_lshl_add_u64 v[42:43], v[30:31], 0, v[42:43]
	global_load_dword v232, v[44:45], off
	global_load_dword v233, v[42:43], off
	v_mad_u64_u32 v[210:211], s[10:11], v34, s22, v[2:3]
	v_mad_u64_u32 v[212:213], s[10:11], v29, s22, v[2:3]
	s_add_i32 s10, s8, 16
	s_add_i32 s9, s7, 16
	v_or_b32_e32 v29, s9, v1
	v_or_b32_e32 v34, s10, v0
	v_or_b32_e32 v44, s10, v32
	v_or_b32_e32 v42, s9, v3
	v_ashrrev_i32_e32 v45, 31, v44
	v_ashrrev_i32_e32 v43, 31, v42
	v_lshlrev_b64 v[44:45], 12, v[44:45]
	v_lshlrev_b64 v[42:43], 12, v[42:43]
	v_lshl_add_u64 v[44:45], v[30:31], 0, v[44:45]
	v_lshl_add_u64 v[42:43], v[30:31], 0, v[42:43]
	global_load_dword v234, v[44:45], off
	global_load_dword v235, v[42:43], off
	v_mad_u64_u32 v[214:215], s[10:11], v34, s22, v[2:3]
	v_mad_u64_u32 v[216:217], s[10:11], v29, s22, v[2:3]
	s_add_i32 s10, s8, 20
	s_add_i32 s9, s7, 20
	v_or_b32_e32 v29, s9, v1
	v_or_b32_e32 v34, s10, v0
	v_or_b32_e32 v44, s10, v32
	v_or_b32_e32 v42, s9, v3
	v_ashrrev_i32_e32 v45, 31, v44
	v_ashrrev_i32_e32 v43, 31, v42
	v_lshlrev_b64 v[44:45], 12, v[44:45]
	v_lshlrev_b64 v[42:43], 12, v[42:43]
	v_lshl_add_u64 v[44:45], v[30:31], 0, v[44:45]
	v_lshl_add_u64 v[42:43], v[30:31], 0, v[42:43]
	global_load_dword v240, v[44:45], off
	global_load_dword v241, v[42:43], off
	v_mad_u64_u32 v[218:219], s[10:11], v34, s22, v[2:3]
	v_mad_u64_u32 v[220:221], s[10:11], v29, s22, v[2:3]
	s_add_i32 s10, s8, 24
	s_add_i32 s9, s7, 24
	v_or_b32_e32 v29, s9, v1
	v_or_b32_e32 v34, s10, v0
	s_add_i32 s8, s8, 28
	s_add_i32 s7, s7, 28
	s_cmp_lg_u32 s6, 0
	v_or_b32_e32 v44, s10, v32
	v_or_b32_e32 v42, s9, v3
	v_ashrrev_i32_e32 v45, 31, v44
	v_ashrrev_i32_e32 v43, 31, v42
	v_lshlrev_b64 v[44:45], 12, v[44:45]
	v_lshlrev_b64 v[42:43], 12, v[42:43]
	v_lshl_add_u64 v[44:45], v[30:31], 0, v[44:45]
	v_lshl_add_u64 v[42:43], v[30:31], 0, v[42:43]
	global_load_dword v242, v[44:45], off
	global_load_dword v243, v[42:43], off
	v_mad_u64_u32 v[222:223], s[10:11], v34, s22, v[2:3]
	v_mad_u64_u32 v[224:225], s[10:11], v29, s22, v[2:3]
	v_or_b32_e32 v34, s8, v0
	v_or_b32_e32 v29, s7, v1
	v_or_b32_e32 v44, s8, v32
	v_or_b32_e32 v42, s7, v3
	v_ashrrev_i32_e32 v45, 31, v44
	v_ashrrev_i32_e32 v43, 31, v42
	v_lshlrev_b64 v[44:45], 12, v[44:45]
	v_lshlrev_b64 v[42:43], 12, v[42:43]
	v_lshl_add_u64 v[44:45], v[30:31], 0, v[44:45]
	v_lshl_add_u64 v[42:43], v[30:31], 0, v[42:43]
	global_load_dword v41, v[44:45], off
	global_load_dword v46, v[42:43], off
	v_mad_u64_u32 v[42:43], s[8:9], v34, s22, v[2:3]
	v_mad_u64_u32 v[44:45], s[8:9], v29, s22, v[2:3]
	s_waitcnt vmcnt(14)
	ds_write_b32 v196, v226
	ds_write_b32 v198, v227
	s_waitcnt vmcnt(12)
	ds_write_b32 v200, v228
	ds_write_b32 v202, v229
	s_waitcnt vmcnt(10)
	ds_write_b32 v206, v230
	ds_write_b32 v208, v231
	s_waitcnt vmcnt(8)
	ds_write_b32 v210, v232
	ds_write_b32 v212, v233
	s_waitcnt vmcnt(6)
	ds_write_b32 v214, v234
	ds_write_b32 v216, v235
	s_waitcnt vmcnt(4)
	ds_write_b32 v218, v240
	ds_write_b32 v220, v241
	s_waitcnt vmcnt(2)
	ds_write_b32 v222, v242
	ds_write_b32 v224, v243
	s_waitcnt vmcnt(0)
	ds_write_b32 v42, v41
	ds_write_b32 v44, v46
	s_cbranch_scc1 .LBB0_322
	s_waitcnt lgkmcnt(0)
	ds_read2_b32 v[44:45], v37 offset0:33 offset1:41
	ds_read2_b32 v[46:47], v37 offset1:8
	ds_read2_b32 v[48:49], v37 offset0:66 offset1:74
	ds_read2_b32 v[50:51], v37 offset0:99 offset1:107
	ds_read2_b32 v[52:53], v37 offset0:132 offset1:140
	ds_read2_b32 v[54:55], v37 offset0:165 offset1:173
	ds_read2_b32 v[56:57], v37 offset0:198 offset1:206
	ds_read2_b32 v[58:59], v37 offset0:231 offset1:239
	v_mov_b32_e32 v29, v161
	v_or_b32_e32 v3, v33, v36
	v_lshl_add_u64 v[42:43], v[28:29], 1, v[10:11]
	v_lshlrev_b32_e32 v160, 11, v3
	v_or_b32_e32 v3, v33, v38
	s_waitcnt lgkmcnt(0)
	v_cvt_pk_bf16_f32 v28, v46, v44
	v_cvt_pk_bf16_f32 v29, v48, v50
	v_cvt_pk_bf16_f32 v30, v52, v54
	v_cvt_pk_bf16_f32 v31, v56, v58
	v_lshl_add_u64 v[60:61], v[42:43], 0, v[160:161]
	v_lshlrev_b32_e32 v160, 11, v3
	global_store_dwordx4 v[60:61], v[28:31], off
	v_or_b32_e32 v3, v33, v39
	s_nop 0
	v_cvt_pk_bf16_f32 v28, v47, v45
	v_cvt_pk_bf16_f32 v29, v49, v51
	v_cvt_pk_bf16_f32 v30, v53, v55
	v_cvt_pk_bf16_f32 v31, v57, v59
	v_lshl_add_u64 v[44:45], v[42:43], 0, v[160:161]
	global_store_dwordx4 v[44:45], v[28:31], off
	ds_read2_b32 v[44:45], v37 offset0:49 offset1:57
	ds_read2_b32 v[46:47], v37 offset0:16 offset1:24
	ds_read2_b32 v[48:49], v37 offset0:82 offset1:90
	ds_read2_b32 v[50:51], v37 offset0:115 offset1:123
	ds_read2_b32 v[52:53], v37 offset0:148 offset1:156
	ds_read2_b32 v[54:55], v37 offset0:181 offset1:189
	ds_read2_b32 v[56:57], v37 offset0:214 offset1:222
	ds_read2_b32 v[58:59], v37 offset0:247 offset1:255
	v_lshlrev_b32_e32 v160, 11, v3
	v_or_b32_e32 v3, v33, v40
	s_waitcnt lgkmcnt(6)
	v_cvt_pk_bf16_f32 v28, v46, v44
	s_waitcnt lgkmcnt(4)
	v_cvt_pk_bf16_f32 v29, v48, v50
	s_waitcnt lgkmcnt(2)
	v_cvt_pk_bf16_f32 v30, v52, v54
	s_waitcnt lgkmcnt(0)
	v_cvt_pk_bf16_f32 v31, v56, v58
	v_lshl_add_u64 v[60:61], v[42:43], 0, v[160:161]
	v_lshlrev_b32_e32 v160, 11, v3
	global_store_dwordx4 v[60:61], v[28:31], off
	v_lshl_add_u64 v[32:33], v[42:43], 0, v[160:161]
	s_nop 0
	v_cvt_pk_bf16_f32 v28, v47, v45
	v_cvt_pk_bf16_f32 v29, v49, v51
	v_cvt_pk_bf16_f32 v30, v53, v55
	v_cvt_pk_bf16_f32 v31, v57, v59
	global_store_dwordx4 v[32:33], v[28:31], off
	s_waitcnt lgkmcnt(0)

.LBB0_327:
	s_lshl_b32 s8, s5, 1
	s_lshl_b32 s7, s4, 1
	v_or_b32_e32 v44, s8, v32
	v_or_b32_e32 v42, s7, v3
	v_ashrrev_i32_e32 v45, 31, v44
	v_ashrrev_i32_e32 v43, 31, v42
	v_lshlrev_b64 v[44:45], 12, v[44:45]
	v_lshlrev_b64 v[42:43], 12, v[42:43]
	v_lshl_add_u64 v[44:45], v[30:31], 0, v[44:45]
	v_lshl_add_u64 v[42:43], v[30:31], 0, v[42:43]
	global_load_dword v226, v[44:45], off
	global_load_dword v227, v[42:43], off
	v_or_b32_e32 v29, s7, v1
	v_or_b32_e32 v34, s8, v0
	v_mad_u64_u32 v[196:197], s[10:11], v34, s22, v[2:3]
	v_mad_u64_u32 v[198:199], s[10:11], v29, s22, v[2:3]
	s_add_i32 s10, s8, 4
	s_add_i32 s9, s7, 4
	v_or_b32_e32 v29, s9, v1
	v_or_b32_e32 v34, s10, v0
	s_add_i32 s5, s5, 16
	s_add_i32 s4, s4, 16
	s_add_i32 s6, s6, -16
	v_or_b32_e32 v44, s10, v32
	v_or_b32_e32 v42, s9, v3
	v_ashrrev_i32_e32 v45, 31, v44
	v_ashrrev_i32_e32 v43, 31, v42
	v_lshlrev_b64 v[44:45], 12, v[44:45]
	v_lshlrev_b64 v[42:43], 12, v[42:43]
	v_lshl_add_u64 v[44:45], v[30:31], 0, v[44:45]
	v_lshl_add_u64 v[42:43], v[30:31], 0, v[42:43]
	global_load_dword v228, v[44:45], off
	global_load_dword v229, v[42:43], off
	v_mad_u64_u32 v[200:201], s[10:11], v34, s22, v[2:3]
	v_mad_u64_u32 v[202:203], s[10:11], v29, s22, v[2:3]
	s_add_i32 s10, s8, 8
	s_add_i32 s9, s7, 8
	v_or_b32_e32 v29, s9, v1
	v_or_b32_e32 v34, s10, v0
	v_or_b32_e32 v44, s10, v32
	v_or_b32_e32 v42, s9, v3
	v_ashrrev_i32_e32 v45, 31, v44
	v_ashrrev_i32_e32 v43, 31, v42
	v_lshlrev_b64 v[44:45], 12, v[44:45]
	v_lshlrev_b64 v[42:43], 12, v[42:43]
	v_lshl_add_u64 v[44:45], v[30:31], 0, v[44:45]
	v_lshl_add_u64 v[42:43], v[30:31], 0, v[42:43]
	global_load_dword v230, v[44:45], off
	global_load_dword v231, v[42:43], off
	v_mad_u64_u32 v[206:207], s[10:11], v34, s22, v[2:3]
	v_mad_u64_u32 v[208:209], s[10:11], v29, s22, v[2:3]
	s_add_i32 s10, s8, 12
	s_add_i32 s9, s7, 12
	v_or_b32_e32 v29, s9, v1
	v_or_b32_e32 v34, s10, v0
	v_or_b32_e32 v44, s10, v32
	v_or_b32_e32 v42, s9, v3
	v_ashrrev_i32_e32 v45, 31, v44
	v_ashrrev_i32_e32 v43, 31, v42
	v_lshlrev_b64 v[44:45], 12, v[44:45]
	v_lshlrev_b64 v[42:43], 12, v[42:43]
	v_lshl_add_u64 v[44:45], v[30:31], 0, v[44:45]
	v_lshl_add_u64 v[42:43], v[30:31], 0, v[42:43]
	global_load_dword v232, v[44:45], off
	global_load_dword v233, v[42:43], off
	v_mad_u64_u32 v[210:211], s[10:11], v34, s22, v[2:3]
	v_mad_u64_u32 v[212:213], s[10:11], v29, s22, v[2:3]
	s_add_i32 s10, s8, 16
	s_add_i32 s9, s7, 16
	v_or_b32_e32 v29, s9, v1
	v_or_b32_e32 v34, s10, v0
	v_or_b32_e32 v44, s10, v32
	v_or_b32_e32 v42, s9, v3
	v_ashrrev_i32_e32 v45, 31, v44
	v_ashrrev_i32_e32 v43, 31, v42
	v_lshlrev_b64 v[44:45], 12, v[44:45]
	v_lshlrev_b64 v[42:43], 12, v[42:43]
	v_lshl_add_u64 v[44:45], v[30:31], 0, v[44:45]
	v_lshl_add_u64 v[42:43], v[30:31], 0, v[42:43]
	global_load_dword v234, v[44:45], off
	global_load_dword v235, v[42:43], off
	v_mad_u64_u32 v[214:215], s[10:11], v34, s22, v[2:3]
	v_mad_u64_u32 v[216:217], s[10:11], v29, s22, v[2:3]
	s_add_i32 s10, s8, 20
	s_add_i32 s9, s7, 20
	v_or_b32_e32 v29, s9, v1
	v_or_b32_e32 v34, s10, v0
	v_or_b32_e32 v44, s10, v32
	v_or_b32_e32 v42, s9, v3
	v_ashrrev_i32_e32 v45, 31, v44
	v_ashrrev_i32_e32 v43, 31, v42
	v_lshlrev_b64 v[44:45], 12, v[44:45]
	v_lshlrev_b64 v[42:43], 12, v[42:43]
	v_lshl_add_u64 v[44:45], v[30:31], 0, v[44:45]
	v_lshl_add_u64 v[42:43], v[30:31], 0, v[42:43]
	global_load_dword v240, v[44:45], off
	global_load_dword v241, v[42:43], off
	v_mad_u64_u32 v[218:219], s[10:11], v34, s22, v[2:3]
	v_mad_u64_u32 v[220:221], s[10:11], v29, s22, v[2:3]
	s_add_i32 s10, s8, 24
	s_add_i32 s9, s7, 24
	v_or_b32_e32 v29, s9, v1
	v_or_b32_e32 v34, s10, v0
	s_add_i32 s8, s8, 28
	s_add_i32 s7, s7, 28
	s_cmp_lg_u32 s6, 0
	v_or_b32_e32 v44, s10, v32
	v_or_b32_e32 v42, s9, v3
	v_ashrrev_i32_e32 v45, 31, v44
	v_ashrrev_i32_e32 v43, 31, v42
	v_lshlrev_b64 v[44:45], 12, v[44:45]
	v_lshlrev_b64 v[42:43], 12, v[42:43]
	v_lshl_add_u64 v[44:45], v[30:31], 0, v[44:45]
	v_lshl_add_u64 v[42:43], v[30:31], 0, v[42:43]
	global_load_dword v242, v[44:45], off
	global_load_dword v243, v[42:43], off
	v_mad_u64_u32 v[222:223], s[10:11], v34, s22, v[2:3]
	v_mad_u64_u32 v[224:225], s[10:11], v29, s22, v[2:3]
	v_or_b32_e32 v34, s8, v0
	v_or_b32_e32 v29, s7, v1
	v_or_b32_e32 v44, s8, v32
	v_or_b32_e32 v42, s7, v3
	v_ashrrev_i32_e32 v45, 31, v44
	v_ashrrev_i32_e32 v43, 31, v42
	v_lshlrev_b64 v[44:45], 12, v[44:45]
	v_lshlrev_b64 v[42:43], 12, v[42:43]
	v_lshl_add_u64 v[44:45], v[30:31], 0, v[44:45]
	v_lshl_add_u64 v[42:43], v[30:31], 0, v[42:43]
	global_load_dword v41, v[44:45], off
	global_load_dword v46, v[42:43], off
	v_mad_u64_u32 v[42:43], s[8:9], v34, s22, v[2:3]
	v_mad_u64_u32 v[44:45], s[8:9], v29, s22, v[2:3]
	s_waitcnt vmcnt(14)
	ds_write_b32 v196, v226
	ds_write_b32 v198, v227
	s_waitcnt vmcnt(12)
	ds_write_b32 v200, v228
	ds_write_b32 v202, v229
	s_waitcnt vmcnt(10)
	ds_write_b32 v206, v230
	ds_write_b32 v208, v231
	s_waitcnt vmcnt(8)
	ds_write_b32 v210, v232
	ds_write_b32 v212, v233
	s_waitcnt vmcnt(6)
	ds_write_b32 v214, v234
	ds_write_b32 v216, v235
	s_waitcnt vmcnt(4)
	ds_write_b32 v218, v240
	ds_write_b32 v220, v241
	s_waitcnt vmcnt(2)
	ds_write_b32 v222, v242
	ds_write_b32 v224, v243
	s_waitcnt vmcnt(0)
	ds_write_b32 v42, v41
	ds_write_b32 v44, v46
	s_cbranch_scc1 .LBB0_327
	s_waitcnt lgkmcnt(0)
	ds_read2_b32 v[44:45], v37 offset0:33 offset1:41
	ds_read2_b32 v[46:47], v37 offset1:8
	ds_read2_b32 v[48:49], v37 offset0:66 offset1:74
	ds_read2_b32 v[50:51], v37 offset0:99 offset1:107
	ds_read2_b32 v[52:53], v37 offset0:132 offset1:140
	ds_read2_b32 v[54:55], v37 offset0:165 offset1:173
	ds_read2_b32 v[56:57], v37 offset0:198 offset1:206
	ds_read2_b32 v[58:59], v37 offset0:231 offset1:239
	v_mov_b32_e32 v29, v161
	v_or_b32_e32 v3, v33, v36
	v_lshl_add_u64 v[42:43], v[28:29], 1, v[12:13]
	v_lshlrev_b32_e32 v160, 11, v3
	v_or_b32_e32 v3, v33, v38
	s_waitcnt lgkmcnt(0)
	v_cvt_pk_bf16_f32 v28, v46, v44
	v_cvt_pk_bf16_f32 v29, v48, v50
	v_cvt_pk_bf16_f32 v30, v52, v54
	v_cvt_pk_bf16_f32 v31, v56, v58
	v_lshl_add_u64 v[60:61], v[42:43], 0, v[160:161]
	v_lshlrev_b32_e32 v160, 11, v3
	global_store_dwordx4 v[60:61], v[28:31], off
	v_or_b32_e32 v3, v33, v39
	s_nop 0
	v_cvt_pk_bf16_f32 v28, v47, v45
	v_cvt_pk_bf16_f32 v29, v49, v51
	v_cvt_pk_bf16_f32 v30, v53, v55
	v_cvt_pk_bf16_f32 v31, v57, v59
	v_lshl_add_u64 v[44:45], v[42:43], 0, v[160:161]
	global_store_dwordx4 v[44:45], v[28:31], off
	ds_read2_b32 v[44:45], v37 offset0:49 offset1:57
	ds_read2_b32 v[46:47], v37 offset0:16 offset1:24
	ds_read2_b32 v[48:49], v37 offset0:82 offset1:90
	ds_read2_b32 v[50:51], v37 offset0:115 offset1:123
	ds_read2_b32 v[52:53], v37 offset0:148 offset1:156
	ds_read2_b32 v[54:55], v37 offset0:181 offset1:189
	ds_read2_b32 v[56:57], v37 offset0:214 offset1:222
	ds_read2_b32 v[58:59], v37 offset0:247 offset1:255
	v_lshlrev_b32_e32 v160, 11, v3
	v_or_b32_e32 v3, v33, v40
	s_waitcnt lgkmcnt(6)
	v_cvt_pk_bf16_f32 v28, v46, v44
	s_waitcnt lgkmcnt(4)
	v_cvt_pk_bf16_f32 v29, v48, v50
	s_waitcnt lgkmcnt(2)
	v_cvt_pk_bf16_f32 v30, v52, v54
	s_waitcnt lgkmcnt(0)
	v_cvt_pk_bf16_f32 v31, v56, v58
	v_lshl_add_u64 v[60:61], v[42:43], 0, v[160:161]
	v_lshlrev_b32_e32 v160, 11, v3
	global_store_dwordx4 v[60:61], v[28:31], off
	v_lshl_add_u64 v[32:33], v[42:43], 0, v[160:161]
	s_nop 0
	v_cvt_pk_bf16_f32 v28, v47, v45
	v_cvt_pk_bf16_f32 v29, v49, v51
	v_cvt_pk_bf16_f32 v30, v53, v55
	v_cvt_pk_bf16_f32 v31, v57, v59
	global_store_dwordx4 v[32:33], v[28:31], off
	s_waitcnt lgkmcnt(0)

.LBB0_332:
	s_lshl_b32 s8, s5, 1
	s_lshl_b32 s7, s4, 1
	v_or_b32_e32 v42, s8, v34
	v_or_b32_e32 v41, s7, v3
	v_mad_i64_i32 v[42:43], s[10:11], v42, s24, v[32:33]
	v_mad_i64_i32 v[44:45], s[10:11], v41, s24, v[32:33]
	global_load_dword v226, v[42:43], off
	global_load_dword v227, v[44:45], off
	v_or_b32_e32 v29, s7, v1
	v_or_b32_e32 v31, s8, v0
	v_mad_u64_u32 v[196:197], s[10:11], v31, s22, v[2:3]
	v_mad_u64_u32 v[198:199], s[10:11], v29, s22, v[2:3]
	s_add_i32 s10, s8, 4
	s_add_i32 s9, s7, 4
	v_or_b32_e32 v31, s10, v0
	v_or_b32_e32 v29, s9, v1
	s_add_i32 s5, s5, 16
	s_add_i32 s4, s4, 16
	s_add_i32 s6, s6, -16
	v_or_b32_e32 v42, s10, v34
	v_or_b32_e32 v41, s9, v3
	v_mad_i64_i32 v[42:43], s[10:11], v42, s24, v[32:33]
	v_mad_i64_i32 v[44:45], s[10:11], v41, s24, v[32:33]
	global_load_dword v228, v[42:43], off
	global_load_dword v229, v[44:45], off
	v_mad_u64_u32 v[200:201], s[10:11], v31, s22, v[2:3]
	v_mad_u64_u32 v[202:203], s[10:11], v29, s22, v[2:3]
	s_add_i32 s10, s8, 8
	s_add_i32 s9, s7, 8
	v_or_b32_e32 v31, s10, v0
	v_or_b32_e32 v29, s9, v1
	v_or_b32_e32 v42, s10, v34
	v_or_b32_e32 v41, s9, v3
	v_mad_i64_i32 v[42:43], s[10:11], v42, s24, v[32:33]
	v_mad_i64_i32 v[44:45], s[10:11], v41, s24, v[32:33]
	global_load_dword v230, v[42:43], off
	global_load_dword v231, v[44:45], off
	v_mad_u64_u32 v[206:207], s[10:11], v31, s22, v[2:3]
	v_mad_u64_u32 v[208:209], s[10:11], v29, s22, v[2:3]
	s_add_i32 s10, s8, 12
	s_add_i32 s9, s7, 12
	v_or_b32_e32 v31, s10, v0
	v_or_b32_e32 v29, s9, v1
	v_or_b32_e32 v42, s10, v34
	v_or_b32_e32 v41, s9, v3
	v_mad_i64_i32 v[42:43], s[10:11], v42, s24, v[32:33]
	v_mad_i64_i32 v[44:45], s[10:11], v41, s24, v[32:33]
	global_load_dword v232, v[42:43], off
	global_load_dword v233, v[44:45], off
	v_mad_u64_u32 v[210:211], s[10:11], v31, s22, v[2:3]
	v_mad_u64_u32 v[212:213], s[10:11], v29, s22, v[2:3]
	s_add_i32 s10, s8, 16
	s_add_i32 s9, s7, 16
	v_or_b32_e32 v31, s10, v0
	v_or_b32_e32 v29, s9, v1
	v_or_b32_e32 v42, s10, v34
	v_or_b32_e32 v41, s9, v3
	v_mad_i64_i32 v[42:43], s[10:11], v42, s24, v[32:33]
	v_mad_i64_i32 v[44:45], s[10:11], v41, s24, v[32:33]
	global_load_dword v234, v[42:43], off
	global_load_dword v235, v[44:45], off
	v_mad_u64_u32 v[214:215], s[10:11], v31, s22, v[2:3]
	v_mad_u64_u32 v[216:217], s[10:11], v29, s22, v[2:3]
	s_add_i32 s10, s8, 20
	s_add_i32 s9, s7, 20
	v_or_b32_e32 v31, s10, v0
	v_or_b32_e32 v29, s9, v1
	v_or_b32_e32 v42, s10, v34
	v_or_b32_e32 v41, s9, v3
	v_mad_i64_i32 v[42:43], s[10:11], v42, s24, v[32:33]
	v_mad_i64_i32 v[44:45], s[10:11], v41, s24, v[32:33]
	global_load_dword v240, v[42:43], off
	global_load_dword v241, v[44:45], off
	v_mad_u64_u32 v[218:219], s[10:11], v31, s22, v[2:3]
	v_mad_u64_u32 v[220:221], s[10:11], v29, s22, v[2:3]
	s_add_i32 s10, s8, 24
	s_add_i32 s9, s7, 24
	v_or_b32_e32 v31, s10, v0
	v_or_b32_e32 v29, s9, v1
	s_add_i32 s8, s8, 28
	s_add_i32 s7, s7, 28
	s_cmp_lg_u32 s6, 0
	v_or_b32_e32 v42, s10, v34
	v_or_b32_e32 v41, s9, v3
	v_mad_i64_i32 v[42:43], s[10:11], v42, s24, v[32:33]
	v_mad_i64_i32 v[44:45], s[10:11], v41, s24, v[32:33]
	global_load_dword v242, v[42:43], off
	global_load_dword v243, v[44:45], off
	v_mad_u64_u32 v[222:223], s[10:11], v31, s22, v[2:3]
	v_mad_u64_u32 v[224:225], s[10:11], v29, s22, v[2:3]
	v_or_b32_e32 v31, s8, v0
	v_or_b32_e32 v29, s7, v1
	v_or_b32_e32 v42, s8, v34
	v_or_b32_e32 v41, s7, v3
	v_mad_i64_i32 v[42:43], s[8:9], v42, s24, v[32:33]
	v_mad_i64_i32 v[44:45], s[8:9], v41, s24, v[32:33]
	global_load_dword v41, v[42:43], off
	global_load_dword v46, v[44:45], off
	v_mad_u64_u32 v[42:43], s[8:9], v31, s22, v[2:3]
	v_mad_u64_u32 v[44:45], s[8:9], v29, s22, v[2:3]
	s_waitcnt vmcnt(14)
	ds_write_b32 v196, v226
	ds_write_b32 v198, v227
	s_waitcnt vmcnt(12)
	ds_write_b32 v200, v228
	ds_write_b32 v202, v229
	s_waitcnt vmcnt(10)
	ds_write_b32 v206, v230
	ds_write_b32 v208, v231
	s_waitcnt vmcnt(8)
	ds_write_b32 v210, v232
	ds_write_b32 v212, v233
	s_waitcnt vmcnt(6)
	ds_write_b32 v214, v234
	ds_write_b32 v216, v235
	s_waitcnt vmcnt(4)
	ds_write_b32 v218, v240
	ds_write_b32 v220, v241
	s_waitcnt vmcnt(2)
	ds_write_b32 v222, v242
	ds_write_b32 v224, v243
	s_waitcnt vmcnt(0)
	ds_write_b32 v42, v41
	ds_write_b32 v44, v46
	s_cbranch_scc1 .LBB0_332
	s_waitcnt lgkmcnt(0)
	ds_read2_b32 v[44:45], v37 offset0:33 offset1:41
	ds_read2_b32 v[46:47], v37 offset1:8
	ds_read2_b32 v[48:49], v37 offset0:66 offset1:74
	ds_read2_b32 v[50:51], v37 offset0:99 offset1:107
	ds_read2_b32 v[52:53], v37 offset0:132 offset1:140
	ds_read2_b32 v[54:55], v37 offset0:165 offset1:173
	ds_read2_b32 v[56:57], v37 offset0:198 offset1:206
	ds_read2_b32 v[58:59], v37 offset0:231 offset1:239
	v_or_b32_e32 v60, v28, v36
	v_ashrrev_i32_e32 v31, 31, v30
	v_ashrrev_i32_e32 v61, 31, v60
	v_lshl_add_u64 v[42:43], v[30:31], 1, v[14:15]
	v_lshlrev_b64 v[60:61], 11, v[60:61]
	s_waitcnt lgkmcnt(0)
	v_cvt_pk_bf16_f32 v30, v46, v44
	v_cvt_pk_bf16_f32 v31, v48, v50
	v_cvt_pk_bf16_f32 v32, v52, v54
	v_cvt_pk_bf16_f32 v33, v56, v58
	v_lshl_add_u64 v[60:61], v[42:43], 0, v[60:61]
	v_or_b32_e32 v44, v28, v38
	global_store_dwordx4 v[60:61], v[30:33], off
	v_or_b32_e32 v60, v28, v39
	v_ashrrev_i32_e32 v61, 31, v60
	v_cvt_pk_bf16_f32 v30, v47, v45
	v_ashrrev_i32_e32 v45, 31, v44
	v_lshlrev_b64 v[44:45], 11, v[44:45]
	v_cvt_pk_bf16_f32 v31, v49, v51
	v_cvt_pk_bf16_f32 v32, v53, v55
	v_cvt_pk_bf16_f32 v33, v57, v59
	v_lshl_add_u64 v[44:45], v[42:43], 0, v[44:45]
	global_store_dwordx4 v[44:45], v[30:33], off
	ds_read2_b32 v[44:45], v37 offset0:49 offset1:57
	ds_read2_b32 v[46:47], v37 offset0:16 offset1:24
	ds_read2_b32 v[48:49], v37 offset0:82 offset1:90
	ds_read2_b32 v[50:51], v37 offset0:115 offset1:123
	ds_read2_b32 v[52:53], v37 offset0:148 offset1:156
	ds_read2_b32 v[54:55], v37 offset0:181 offset1:189
	ds_read2_b32 v[56:57], v37 offset0:214 offset1:222
	ds_read2_b32 v[58:59], v37 offset0:247 offset1:255
	v_lshlrev_b64 v[60:61], 11, v[60:61]
	s_waitcnt lgkmcnt(6)
	v_cvt_pk_bf16_f32 v30, v46, v44
	s_waitcnt lgkmcnt(4)
	v_cvt_pk_bf16_f32 v31, v48, v50
	s_waitcnt lgkmcnt(2)
	v_cvt_pk_bf16_f32 v32, v52, v54
	s_waitcnt lgkmcnt(0)
	v_cvt_pk_bf16_f32 v33, v56, v58
	v_lshl_add_u64 v[60:61], v[42:43], 0, v[60:61]
	global_store_dwordx4 v[60:61], v[30:33], off
	v_cvt_pk_bf16_f32 v29, v49, v51
	s_nop 0
	v_or_b32_e32 v32, v28, v40
	v_ashrrev_i32_e32 v33, 31, v32
	v_lshlrev_b64 v[32:33], 11, v[32:33]
	v_cvt_pk_bf16_f32 v28, v47, v45
	v_cvt_pk_bf16_f32 v30, v53, v55
	v_cvt_pk_bf16_f32 v31, v57, v59
	v_lshl_add_u64 v[32:33], v[42:43], 0, v[32:33]
	global_store_dwordx4 v[32:33], v[28:31], off
	s_waitcnt lgkmcnt(0)
	s_branch .LBB0_301
